# strategy 4 variant: static priority raise for the LEADING half-workgroup instead of the trailing one (comparison arm)
# baseline (speedup 1.0000x reference)
; #define PG8_STAGE(bufoff, gbase, voff) do { _Pragma("unroll") for (int _i = 0; _i < 2; ++_i) \
;         __builtin_amdgcn_global_load_lds((const unsigned*)((const char*)(gbase) + (voff)[_i]), (PG8_LAS unsigned*)(lds + (bufoff) + ldsw + _i * 8192), 16, 0, 0); } while (0)
; #define PG8_BAR __builtin_amdgcn_s_barrier()
;     __host__ __device__ bool next(int i, Unit& u) const {
;         const long L = (long)i * G + c; if (L >= nwg) return false;
;         int wgid = (int)L; { const int q = nwg / NXCD, r = nwg % NXCD, xcd = wgid % NXCD, off = wgid / NXCD; wgid = (xcd < r ? xcd * (q + 1) : r * (q + 1) + (xcd - r) * q) + off; }
;         const int nig = WGM * nN, gid = wgid / nig, fm = gid * WGM, gsz = (nM - fm) < WGM ? (nM - fm) : WGM;
;         u.pm = fm + ((wgid % nig) % gsz); u.pn = (wgid % nig) / gsz; return true;
; template <class Epi, class Sched, bool ALIGN_EPI = false, bool SP2 = false>
; __device__ __forceinline__ void gemm_phase(PG8_LAS unsigned char* lds, const Gemm g, const Sched& S, const Epi& E) {
;     ...
;     const char* cA = (const char*)g.A + (size_t)cur.pm * tstep; const char* cB = (const char*)g.Bt + (size_t)cur.pn * tstep;
;     S.a_ready(cur);
;     if constexpr (SP2) {
;         PG8_STAGE(PG8_SB(0, 0), cB, voffB); PG8_STAGE(PG8_SB(0, 1), cB + hstep, voffB); PG8_STAGE(PG8_SA(0, 0), cA, voffA); PG8_STAGE(PG8_SA(0, 1), cA + hstep, voffA);
;         if (wr == 1) PG8_BAR;
.LBB0_416:
	s_andn2_b64 vcc, exec, s[24:25]
	s_lshr_b32 s61, s45, 1
	v_writelane_b32 v250, s46, 27
	v_writelane_b32 v250, s45, 28
	s_cbranch_vccnz .LBB0_487
	s_and_b64 s[0:1], s[22:23], exec
	s_movk_i32 s0, 0x400
	s_cselect_b32 s49, s0, 0xa00
	s_lshr_b32 s26, s49, 1
	v_mov_b32_e32 v10, v204
	v_readlane_b32 s0, v252, 0
	s_cmp_ge_i32 s0, s26
	v_readfirstlane_b32 s27, v10
	s_cbranch_scc1 .LBB0_433
	v_lshlrev_b32_e32 v0, 4, v10
	s_waitcnt lgkmcnt(0)
	v_add_u32_e32 v1, 0x2000, v0
	s_waitcnt lgkmcnt(0)
	v_ashrrev_i32_e32 v2, 31, v1
	v_lshrrev_b32_e32 v2, 22, v2
	v_add_u32_e32 v2, v1, v2
	v_ashrrev_i32_e32 v8, 10, v2
	v_mul_i32_i24_e32 v2, 0x400, v8
	v_sub_u32_e32 v1, v1, v2
	v_lshrrev_b32_e32 v2, 4, v1
	v_bitop3_b32 v1, v2, v1, 32 bitop3:0x6c
	v_ashrrev_i32_e32 v2, 31, v1
	s_lshl_b32 s1, s45, 20
	v_lshrrev_b32_e32 v2, 26, v2
	s_mul_i32 s0, s61, 0x380000
	s_and_b32 s1, s1, 0x100000
	v_add_u32_e32 v2, v1, v2
	v_lshlrev_b32_e32 v3, 3, v8
	s_add_i32 s30, s0, s1
	v_ashrrev_i32_e32 v9, 6, v2
	v_and_b32_e32 v3, -16, v3
	s_lshl_b64 s[0:1], s[30:31], 1
	v_add_u32_e32 v3, v9, v3
	s_add_u32 s30, s64, s0
	v_and_b32_e32 v4, 3, v9
	s_mov_b32 s0, 0x1fffe0
	v_lshrrev_b32_e32 v5, 2, v3
	v_lshlrev_b32_e32 v6, 1, v3
	v_and_b32_e32 v2, 0xc0, v2
	v_and_or_b32 v4, v3, s0, v4
	v_and_b32_e32 v5, 4, v5
	v_and_b32_e32 v6, 24, v6
	v_sub_u32_e32 v1, v1, v2
	v_or3_b32 v4, v4, v5, v6
	v_lshlrev_b32_e32 v5, 5, v8
	v_ashrrev_i16_sdwa v1, v205, sext(v1) dst_sel:DWORD dst_unused:UNUSED_PAD src0_sel:DWORD src1_sel:BYTE_0
	v_and_b32_e32 v5, 32, v5
	v_bfe_i32 v11, v1, 0, 16
	v_add_lshl_u32 v1, v5, v11, 1
	v_lshl_add_u32 v128, v4, 11, v1
	v_lshl_add_u32 v130, v3, 11, v1
	v_bfe_i32 v1, v10, 27, 1
	v_lshrrev_b32_e32 v1, 22, v1
	v_add_u32_e32 v1, v0, v1
	v_and_b32_e32 v1, 0xfffffc00, v1
	v_sub_u32_e32 v0, v0, v1
	v_lshrrev_b32_e32 v1, 4, v0
	v_ashrrev_i32_e32 v2, 31, v10
	v_bitop3_b32 v0, v1, v0, 32 bitop3:0x6c
	v_lshrrev_b32_e32 v2, 26, v2
	v_ashrrev_i32_e32 v1, 31, v0
	v_add_u32_e32 v2, v10, v2
	v_lshrrev_b32_e32 v1, 26, v1
	v_ashrrev_i32_e32 v13, 6, v2
	v_add_u32_e32 v1, v0, v1
	v_lshlrev_b32_e32 v2, 3, v13
	v_ashrrev_i32_e32 v12, 6, v1
	v_and_b32_e32 v2, -16, v2
	v_writelane_b32 v250, s52, 29
	v_add_u32_e32 v2, v12, v2
	v_and_b32_e32 v3, 3, v12
	v_writelane_b32 v250, s53, 30
	s_addc_u32 s52, s65, s1
	s_ashr_i32 s23, s27, 6
	v_and_or_b32 v3, v2, s0, v3
	s_lshr_b32 s55, s49, 4
	v_readlane_b32 s0, v251, 34
	s_lshr_b32 s53, s49, 6
	s_ashr_i32 s29, s27, 8
	s_lshl_b32 s54, s23, 10
	s_or_b32 s22, s55, 1
	v_readlane_b32 s1, v251, 35
	s_and_b64 s[0:1], s[0:1], exec
	v_lshrrev_b32_e32 v4, 2, v2
	v_lshlrev_b32_e32 v5, 1, v2
	v_and_b32_e32 v1, 0xc0, v1
	s_cselect_b32 s0, s22, s55
	s_abs_i32 s59, s53
	v_and_b32_e32 v4, 4, v4
	v_and_b32_e32 v5, 24, v5
	v_sub_u32_e32 v0, v0, v1
	v_cvt_f32_u32_e32 v1, s59
	v_or3_b32 v3, v3, v4, v5
	v_lshlrev_b32_e32 v4, 5, v13
	v_ashrrev_i16_sdwa v0, v205, sext(v0) dst_sel:DWORD dst_unused:UNUSED_PAD src0_sel:DWORD src1_sel:BYTE_0
	v_and_b32_e32 v4, 32, v4
	v_bfe_i32 v14, v0, 0, 16
	v_add_lshl_u32 v0, v4, v14, 1
	v_lshl_add_u32 v138, v3, 11, v0
	v_lshl_add_u32 v132, v2, 11, v0
	v_rcp_iflag_f32_e32 v0, v1
	v_readlane_b32 s1, v251, 36
	s_mul_i32 s0, s0, s1
	v_readlane_b32 s1, v251, 37
	v_mul_f32_e32 v0, 0x4f7ffffe, v0
	v_cvt_u32_f32_e32 v0, v0
	s_sub_i32 s24, 0, s59
	v_writelane_b32 v250, s61, 31
	s_add_i32 s0, s0, s1
	v_readfirstlane_b32 s89, v0
	s_mul_i32 s24, s24, s89
	v_writelane_b32 v250, s22, 32
	s_ashr_i32 s1, s0, 31
	s_ashr_i32 s22, s53, 31
	s_mul_hi_u32 s24, s89, s24
	s_mov_b32 s45, s22
	s_xor_b32 s1, s1, s22
	s_abs_i32 s22, s0
	s_add_i32 s89, s89, s24
	s_mul_hi_u32 s24, s22, s89
	s_mul_i32 s25, s24, s59
	s_sub_i32 s22, s22, s25
	s_add_i32 s25, s24, 1
	s_sub_i32 s28, s22, s59
	s_cmp_ge_u32 s22, s59
	s_cselect_b32 s24, s25, s24
	s_cselect_b32 s22, s28, s22
	s_add_i32 s25, s24, 1
	s_cmp_ge_u32 s22, s59
	s_cselect_b32 s22, s25, s24
	s_xor_b32 s22, s22, s1
	s_sub_i32 s1, s22, s1
	s_lshl_b32 s22, s1, 2
	s_sub_i32 s24, 0x80, s22
	s_min_i32 s24, s24, 4
	s_sext_i32_i16 s25, s24
	v_cvt_f32_i32_e32 v0, s25
	s_mul_i32 s1, s1, s53
	s_sub_i32 s36, s0, s1
	v_cvt_f32_i32_e32 v1, s36
	v_rcp_iflag_f32_e32 v2, v0
	s_xor_b32 s0, s36, s25
	s_ashr_i32 s0, s0, 30
	s_or_b32 s25, s0, 1
	v_mul_f32_e32 v2, v1, v2
	v_trunc_f32_e32 v2, v2
	v_fma_f32 v1, -v2, v0, v1
	v_cvt_i32_f32_e32 v2, v2
	v_cmp_ge_f32_e64 s[0:1], |v1|, |v0|
	s_and_b64 s[0:1], s[0:1], exec
	s_cselect_b32 s0, s25, 0
	v_readfirstlane_b32 s1, v2
	s_add_i32 s28, s1, s0
	s_mul_i32 s0, s28, s24
	s_sub_i32 s0, s36, s0
	s_sext_i32_i16 s0, s0
	s_add_i32 s24, s22, s0
	s_ashr_i32 s25, s24, 31
	s_bfe_i64 s[36:37], s[28:29], 0x100000
	s_lshl_b64 s[0:1], s[24:25], 19
	s_lshl_b64 s[36:37], s[36:37], 19
	s_add_u32 s42, s30, s36
	s_addc_u32 s43, s52, s37
	s_add_i32 s48, s54, 0
	s_add_i32 m0, s48, 0x10000
	v_mov_b32_e32 v129, v139
	global_load_lds_dwordx4 v138, s[42:43]
	s_add_i32 m0, s48, 0x12000
	s_add_u32 s36, s42, 0x40000
	global_load_lds_dwordx4 v128, s[42:43]
	s_addc_u32 s37, s43, 0
	s_add_i32 m0, s48, 0x14000
	v_mov_b32_e32 v133, v139
	global_load_lds_dwordx4 v138, s[36:37]
	s_add_i32 m0, s48, 0x16000
	s_add_u32 s46, s72, s0
	s_addc_u32 s47, s73, s1
	s_add_i32 s0, s48, 0x2000
	global_load_lds_dwordx4 v128, s[36:37]
	s_mov_b32 m0, s48
	s_add_u32 s36, s46, 0x40000
	global_load_lds_dwordx4 v132, s[46:47]
	s_mov_b32 m0, s0
	s_addc_u32 s37, s47, 0
	s_add_i32 s1, s48, 0x4000
	global_load_lds_dwordx4 v130, s[46:47]
	s_mov_b32 m0, s1
	s_add_i32 s22, s48, 0x6000
	global_load_lds_dwordx4 v132, s[36:37]
	s_mov_b32 m0, s22
	s_cmp_eq_u32 s29, 1
	global_load_lds_dwordx4 v130, s[36:37]
	v_mov_b32_e32 v131, v139
	s_cselect_b64 s[36:37], -1, 0
	v_lshl_add_u64 v[4:5], s[42:43], 0, v[138:139]
	v_lshl_add_u64 v[2:3], s[42:43], 0, v[128:129]
	v_lshl_add_u64 v[0:1], s[46:47], 0, v[132:133]
	v_writelane_b32 v250, s36, 34
	s_cmp_lg_u32 s29, 1
	v_lshl_add_u64 v[6:7], s[46:47], 0, v[130:131]
	v_writelane_b32 v250, s37, 35
	s_setprio 1
	s_cbranch_scc1 .LBB0_420
	s_setprio 0
	s_barrier

;     __device__ __forceinline__ void operator()(const f32x4 (&acc)[2][2][4][2], const Unit& u, int wr, int wc, int fr, int fq) const {
;         const int row0 = u.pm * BM + wr * 64 + fr, col0 = u.pn * BM + wc * 32 + 8 * fq;
; #pragma unroll
;         for (int ai = 0; ai < 2; ++ai)
; #pragma unroll
;             for (int m = 0; m < 4; ++m) {
;                 const int row = row0 + ai * HALF + m * 16;
;                 const f32x4* sp = (const f32x4*)(ss + (size_t)row * 16);
;                 const f32x4 a0 = sp[0], a1 = sp[1], a2 = sp[2], a3 = sp[3];
;                 const float tot = ((a0.x + a0.y) + (a0.z + a0.w)) + ((a1.x + a1.y) + (a1.z + a1.w)) + ((a2.x + a2.y) + (a2.z + a2.w)) + ((a3.x + a3.y) + (a3.z + a3.w));
;                 const float rs = rsqrtf(tot * (1.0f / 1024.0f) + 1e-6f);
.LBB0_429:
	s_setprio 0
	v_lshl_add_u32 v154, s24, 8, v156
	v_ashrrev_i32_e32 v155, 31, v154
	v_lshlrev_b64 v[234:235], 6, v[154:155]
	v_and_or_b32 v234, v204, 48, v234
	v_lshl_add_u64 v[234:235], s[90:91], 0, v[234:235]
	v_mov_b32_e32 v236, 0x2000
	v_mov_b32_e32 v237, 0
	v_lshl_add_u64 v[236:237], v[234:235], 0, v[236:237]
	global_load_dwordx4 v[180:183], v[234:235], off
	global_load_dwordx4 v[184:187], v[234:235], off offset:1024
	global_load_dwordx4 v[188:191], v[234:235], off offset:2048
	global_load_dwordx4 v[192:195], v[234:235], off offset:3072
	global_load_dwordx4 v[196:199], v[236:237], off
	global_load_dwordx4 v[200:203], v[236:237], off offset:1024
	global_load_dwordx4 v[216:219], v[236:237], off offset:2048
	global_load_dwordx4 v[220:223], v[236:237], off offset:3072
	v_lshl_or_b32 v152, s25, 8, v158
	v_ashrrev_i32_e32 v153, 31, v152
	v_lshlrev_b64 v[152:153], 1, v[152:153]
	v_bfe_u32 v228, v204, 2, 4
	v_and_b32_e32 v229, 15, v204
	v_sub_u32_e32 v229, v228, v229
	v_mul_i32_i24_e32 v229, s49, v229
	v_and_b32_e32 v231, 3, v204
	v_bfe_u32 v232, v204, 4, 2
	v_sub_u32_e32 v232, v231, v232
	v_lshl_add_u32 v229, v232, 3, v229
	v_lshlrev_b32_e32 v232, 1, v229
	v_ashrrev_i32_e32 v233, 31, v232
	v_lshl_add_u64 v[152:153], v[152:153], 0, v[232:233]
	v_lshl_add_u32 v230, v231, 4, v228
	v_lshlrev_b32_e32 v230, 2, v230
	v_readlane_b32 s76, v250, 21
	v_readlane_b32 s92, v250, 23
	v_readlane_b32 s96, v250, 25
	v_readlane_b32 s77, v250, 22
	v_readlane_b32 s93, v250, 24
	v_readlane_b32 s97, v250, 26
	v_mad_i64_i32 v[162:163], s[24:25], v154, s49, 0
	v_lshl_add_u64 v[162:163], v[162:163], 1, s[78:79]
	v_lshl_add_u64 v[162:163], v[162:163], 0, v[152:153]
	s_waitcnt vmcnt(0)
	v_add_f32_e32 v180, v180, v181
	v_add_f32_e32 v182, v182, v183
	v_add_f32_e32 v184, v184, v185
	v_add_f32_e32 v186, v186, v187
	v_add_f32_e32 v188, v188, v189
	v_add_f32_e32 v190, v190, v191
	v_add_f32_e32 v192, v192, v193
	v_add_f32_e32 v194, v194, v195
	v_add_f32_e32 v196, v196, v197
	v_add_f32_e32 v198, v198, v199
	v_add_f32_e32 v200, v200, v201
	v_add_f32_e32 v202, v202, v203
	v_add_f32_e32 v216, v216, v217
	v_add_f32_e32 v218, v218, v219
	v_add_f32_e32 v220, v220, v221
	v_add_f32_e32 v222, v222, v223
	v_add_f32_e32 v180, v180, v182
	v_add_f32_e32 v184, v184, v186
	v_add_f32_e32 v188, v188, v190
	v_add_f32_e32 v192, v192, v194
	v_add_f32_e32 v196, v196, v198
	v_add_f32_e32 v200, v200, v202
	v_add_f32_e32 v216, v216, v218
	v_add_f32_e32 v220, v220, v222
	v_mov_b32_e32 v181, v180
	v_mov_b32_e32 v185, v184
	v_mov_b32_e32 v189, v188
	v_mov_b32_e32 v193, v192
	v_mov_b32_e32 v197, v196
	v_mov_b32_e32 v201, v200
	v_mov_b32_e32 v217, v216
	v_mov_b32_e32 v221, v220
	s_nop 1
	v_permlane16_swap_b32_e32 v180, v181
	v_permlane16_swap_b32_e32 v184, v185
	v_permlane16_swap_b32_e32 v188, v189
	v_permlane16_swap_b32_e32 v192, v193
	v_permlane16_swap_b32_e32 v196, v197
	v_permlane16_swap_b32_e32 v200, v201
	v_permlane16_swap_b32_e32 v216, v217
	v_permlane16_swap_b32_e32 v220, v221
	v_add_f32_e32 v180, v180, v181
	v_add_f32_e32 v184, v184, v185
	v_add_f32_e32 v188, v188, v189
	v_add_f32_e32 v192, v192, v193
	v_add_f32_e32 v196, v196, v197
	v_add_f32_e32 v200, v200, v201
	v_add_f32_e32 v216, v216, v217
	v_add_f32_e32 v220, v220, v221
	v_mov_b32_e32 v181, v180
	v_mov_b32_e32 v185, v184
	v_mov_b32_e32 v189, v188
	v_mov_b32_e32 v193, v192
	v_mov_b32_e32 v197, v196
	v_mov_b32_e32 v201, v200
	v_mov_b32_e32 v217, v216
	v_mov_b32_e32 v221, v220
	s_nop 1
	v_permlane32_swap_b32_e32 v180, v181
	v_permlane32_swap_b32_e32 v184, v185
	v_permlane32_swap_b32_e32 v188, v189
	v_permlane32_swap_b32_e32 v192, v193
	v_permlane32_swap_b32_e32 v196, v197
	v_permlane32_swap_b32_e32 v200, v201
	v_permlane32_swap_b32_e32 v216, v217
	v_permlane32_swap_b32_e32 v220, v221
	v_add_f32_e32 v180, v180, v181
	v_add_f32_e32 v184, v184, v185
	v_add_f32_e32 v188, v188, v189
	v_add_f32_e32 v192, v192, v193
	v_add_f32_e32 v196, v196, v197
	v_add_f32_e32 v200, v200, v201
	v_add_f32_e32 v216, v216, v217
	v_add_f32_e32 v220, v220, v221
	v_fmamk_f32 v180, v180, 0x3a800000, v137
	v_cmp_gt_f32_e32 vcc, s4, v180
	v_mul_f32_e32 v181, 0x4b800000, v180
	s_nop 0
	v_cndmask_b32_e32 v180, v180, v181, vcc
	v_rsq_f32_e32 v180, v180
	s_nop 0
	v_mul_f32_e32 v181, 0x45800000, v180
	v_cndmask_b32_e32 v180, v180, v181, vcc
	v_fmamk_f32 v184, v184, 0x3a800000, v137
	v_cmp_gt_f32_e32 vcc, s4, v184
	v_mul_f32_e32 v185, 0x4b800000, v184
	s_nop 0
	v_cndmask_b32_e32 v184, v184, v185, vcc
	v_rsq_f32_e32 v184, v184
	s_nop 0
	v_mul_f32_e32 v185, 0x45800000, v184
	v_cndmask_b32_e32 v184, v184, v185, vcc
	v_fmamk_f32 v188, v188, 0x3a800000, v137
	v_cmp_gt_f32_e32 vcc, s4, v188
	v_mul_f32_e32 v189, 0x4b800000, v188
	s_nop 0
	v_cndmask_b32_e32 v188, v188, v189, vcc
	v_rsq_f32_e32 v188, v188
	s_nop 0
	v_mul_f32_e32 v189, 0x45800000, v188
	v_cndmask_b32_e32 v188, v188, v189, vcc
	v_fmamk_f32 v192, v192, 0x3a800000, v137
	v_cmp_gt_f32_e32 vcc, s4, v192
	v_mul_f32_e32 v193, 0x4b800000, v192
	s_nop 0
	v_cndmask_b32_e32 v192, v192, v193, vcc
	v_rsq_f32_e32 v192, v192
	s_nop 0
	v_mul_f32_e32 v193, 0x45800000, v192
	v_cndmask_b32_e32 v192, v192, v193, vcc
	v_fmamk_f32 v196, v196, 0x3a800000, v137
	v_cmp_gt_f32_e32 vcc, s4, v196
	v_mul_f32_e32 v197, 0x4b800000, v196
	s_nop 0
	v_cndmask_b32_e32 v196, v196, v197, vcc
	v_rsq_f32_e32 v196, v196
	s_nop 0
	v_mul_f32_e32 v197, 0x45800000, v196
	v_cndmask_b32_e32 v196, v196, v197, vcc
	v_fmamk_f32 v200, v200, 0x3a800000, v137
	v_cmp_gt_f32_e32 vcc, s4, v200
	v_mul_f32_e32 v201, 0x4b800000, v200
	s_nop 0
	v_cndmask_b32_e32 v200, v200, v201, vcc
	v_rsq_f32_e32 v200, v200
	s_nop 0
	v_mul_f32_e32 v201, 0x45800000, v200
; __device__ __forceinline__ unsigned cvt_pk_bf16(float lo, float hi) { unsigned r; asm volatile("v_cvt_pk_bf16_f32 %0, %1, %2" : "=v"(r) : "v"(lo), "v"(hi)); return r; }
;     __device__ __forceinline__ void operator()(const f32x4 (&acc)[2][2][4][2], const Unit& u, int wr, int wc, int fr, int fq) const {
;     ...
;                 const int row = row0 + ai * HALF + m * 16;
;                 const f32x4* sp = (const f32x4*)(ss + (size_t)row * 16);
;                 const f32x4 a0 = sp[0], a1 = sp[1], a2 = sp[2], a3 = sp[3];
;                 const float tot = ((a0.x + a0.y) + (a0.z + a0.w)) + ((a1.x + a1.y) + (a1.z + a1.w)) + ((a2.x + a2.y) + (a2.z + a2.w)) + ((a3.x + a3.y) + (a3.z + a3.w));
;                 const float rs = rsqrtf(tot * (1.0f / 1024.0f) + 1e-6f);
;                 bf16_t* rowp = O + (size_t)row * ldc + col0;
; #pragma unroll
;                 for (int bj = 0; bj < 2; ++bj) {
;                     f32x4 v0 = acc[ai][bj][m][0] * rs, v1 = acc[ai][bj][m][1] * rs;
;                     if (ACT == 1) {
; #pragma unroll
;                         for (int e = 0; e < 4; ++e) { float a = fmaxf(v0[e], 0.f); v0[e] = a * a; float b = fmaxf(v1[e], 0.f); v1[e] = b * b; }
;                     }
;                     u32x4 w; w.x = cvt_pk_bf16(v0[0], v0[1]); w.y = cvt_pk_bf16(v0[2], v0[3]); w.z = cvt_pk_bf16(v1[0], v1[1]); w.w = cvt_pk_bf16(v1[2], v1[3]);
;                     *(u32x4*)(rowp + bj * HALF) = w;
	v_cndmask_b32_e32 v200, v200, v201, vcc
	v_fmamk_f32 v216, v216, 0x3a800000, v137
	v_cmp_gt_f32_e32 vcc, s4, v216
	v_mul_f32_e32 v217, 0x4b800000, v216
	s_nop 0
	v_cndmask_b32_e32 v216, v216, v217, vcc
	v_rsq_f32_e32 v216, v216
	s_nop 0
	v_mul_f32_e32 v217, 0x45800000, v216
	v_cndmask_b32_e32 v216, v216, v217, vcc
	v_fmamk_f32 v220, v220, 0x3a800000, v137
	v_cmp_gt_f32_e32 vcc, s4, v220
	v_mul_f32_e32 v221, 0x4b800000, v220
	s_nop 0
	v_cndmask_b32_e32 v220, v220, v221, vcc
	v_rsq_f32_e32 v220, v220
	s_nop 0
	v_mul_f32_e32 v221, 0x45800000, v220
	v_cndmask_b32_e32 v220, v220, v221, vcc
	v_mov_b32_e32 v160, v180
	v_pk_mul_f32 v[126:127], v[126:127], v[160:161] op_sel_hi:[1,0]
	v_pk_mul_f32 v[124:125], v[124:125], v[160:161] op_sel_hi:[1,0]
	v_pk_mul_f32 v[164:165], v[122:123], v[160:161] op_sel_hi:[1,0]
	v_pk_mul_f32 v[122:123], v[120:121], v[160:161] op_sel_hi:[1,0]
	v_cvt_pk_bf16_f32 v120, v124, v125
	v_cvt_pk_bf16_f32 v121, v126, v127
	v_pk_mul_f32 v[118:119], v[118:119], v[160:161] op_sel_hi:[1,0]
	v_cvt_pk_bf16_f32 v122, v122, v123
	v_cvt_pk_bf16_f32 v123, v164, v165
	ds_bpermute_b32 v208, v230, v120
	ds_bpermute_b32 v209, v230, v121
	ds_bpermute_b32 v210, v230, v122
	ds_bpermute_b32 v211, v230, v123
	v_pk_mul_f32 v[116:117], v[116:117], v[160:161] op_sel_hi:[1,0]
	s_nop 0
	v_pk_mul_f32 v[120:121], v[114:115], v[160:161] op_sel_hi:[1,0]
	v_pk_mul_f32 v[114:115], v[112:113], v[160:161] op_sel_hi:[1,0]
	v_or_b32_e32 v160, 16, v154
	v_cvt_pk_bf16_f32 v112, v116, v117
	v_cvt_pk_bf16_f32 v113, v118, v119
	v_ashrrev_i32_e32 v161, 31, v160
	v_cvt_pk_bf16_f32 v114, v114, v115
	v_cvt_pk_bf16_f32 v115, v120, v121
	ds_bpermute_b32 v212, v230, v112
	ds_bpermute_b32 v213, v230, v113
	ds_bpermute_b32 v214, v230, v114
	ds_bpermute_b32 v215, v230, v115
	s_waitcnt lgkmcnt(4)
	global_store_dwordx4 v[162:163], v[208:211], off
	s_waitcnt lgkmcnt(0)
	global_store_dwordx4 v[162:163], v[212:215], off offset:256
	s_nop 1
	v_mad_i64_i32 v[114:115], s[24:25], v160, s49, 0
	v_lshl_add_u64 v[114:115], v[114:115], 1, s[78:79]
	v_lshl_add_u64 v[114:115], v[114:115], 0, v[152:153]
	v_mov_b32_e32 v112, v184
	v_pk_mul_f32 v[110:111], v[110:111], v[112:113] op_sel_hi:[1,0]
	v_pk_mul_f32 v[108:109], v[108:109], v[112:113] op_sel_hi:[1,0]
	v_pk_mul_f32 v[116:117], v[106:107], v[112:113] op_sel_hi:[1,0]
	v_pk_mul_f32 v[106:107], v[104:105], v[112:113] op_sel_hi:[1,0]
	v_cvt_pk_bf16_f32 v104, v108, v109
	v_cvt_pk_bf16_f32 v105, v110, v111
	v_pk_mul_f32 v[102:103], v[102:103], v[112:113] op_sel_hi:[1,0]
	v_cvt_pk_bf16_f32 v106, v106, v107
	v_cvt_pk_bf16_f32 v107, v116, v117
	ds_bpermute_b32 v208, v230, v104
	ds_bpermute_b32 v209, v230, v105
	ds_bpermute_b32 v210, v230, v106
	ds_bpermute_b32 v211, v230, v107
	v_pk_mul_f32 v[100:101], v[100:101], v[112:113] op_sel_hi:[1,0]
	s_nop 0
	v_pk_mul_f32 v[104:105], v[98:99], v[112:113] op_sel_hi:[1,0]
	v_pk_mul_f32 v[98:99], v[96:97], v[112:113] op_sel_hi:[1,0]
	v_or_b32_e32 v112, 32, v154
	v_cvt_pk_bf16_f32 v96, v100, v101
	v_cvt_pk_bf16_f32 v97, v102, v103
	v_ashrrev_i32_e32 v113, 31, v112
	v_cvt_pk_bf16_f32 v98, v98, v99
	v_cvt_pk_bf16_f32 v99, v104, v105
	ds_bpermute_b32 v212, v230, v96
	ds_bpermute_b32 v213, v230, v97
	ds_bpermute_b32 v214, v230, v98
	ds_bpermute_b32 v215, v230, v99
	s_waitcnt lgkmcnt(4)
	global_store_dwordx4 v[114:115], v[208:211], off
	s_waitcnt lgkmcnt(0)
	global_store_dwordx4 v[114:115], v[212:215], off offset:256
	s_nop 1
	v_mad_i64_i32 v[98:99], s[24:25], v112, s49, 0
	v_lshl_add_u64 v[98:99], v[98:99], 1, s[78:79]
	v_lshl_add_u64 v[98:99], v[98:99], 0, v[152:153]
	v_mov_b32_e32 v96, v188
	v_pk_mul_f32 v[94:95], v[94:95], v[96:97] op_sel_hi:[1,0]
	v_pk_mul_f32 v[92:93], v[92:93], v[96:97] op_sel_hi:[1,0]
	v_pk_mul_f32 v[100:101], v[90:91], v[96:97] op_sel_hi:[1,0]
	v_pk_mul_f32 v[90:91], v[88:89], v[96:97] op_sel_hi:[1,0]
	v_cvt_pk_bf16_f32 v88, v92, v93
	v_cvt_pk_bf16_f32 v89, v94, v95
	v_pk_mul_f32 v[86:87], v[86:87], v[96:97] op_sel_hi:[1,0]
	v_cvt_pk_bf16_f32 v90, v90, v91
	v_cvt_pk_bf16_f32 v91, v100, v101
	ds_bpermute_b32 v208, v230, v88
	ds_bpermute_b32 v209, v230, v89
	ds_bpermute_b32 v210, v230, v90
	ds_bpermute_b32 v211, v230, v91
	v_pk_mul_f32 v[84:85], v[84:85], v[96:97] op_sel_hi:[1,0]
	s_nop 0
	v_pk_mul_f32 v[88:89], v[82:83], v[96:97] op_sel_hi:[1,0]
	v_pk_mul_f32 v[82:83], v[80:81], v[96:97] op_sel_hi:[1,0]
	v_or_b32_e32 v96, 48, v154
	v_cvt_pk_bf16_f32 v80, v84, v85
	v_cvt_pk_bf16_f32 v81, v86, v87
	v_ashrrev_i32_e32 v97, 31, v96
	v_cvt_pk_bf16_f32 v82, v82, v83
	v_cvt_pk_bf16_f32 v83, v88, v89
	ds_bpermute_b32 v212, v230, v80
	ds_bpermute_b32 v213, v230, v81
	ds_bpermute_b32 v214, v230, v82
	ds_bpermute_b32 v215, v230, v83
	s_waitcnt lgkmcnt(4)
	global_store_dwordx4 v[98:99], v[208:211], off
	s_waitcnt lgkmcnt(0)
	global_store_dwordx4 v[98:99], v[212:215], off offset:256
	s_nop 1
	v_mad_i64_i32 v[82:83], s[24:25], v96, s49, 0
	v_lshl_add_u64 v[82:83], v[82:83], 1, s[78:79]
	v_lshl_add_u64 v[82:83], v[82:83], 0, v[152:153]
	v_mov_b32_e32 v80, v192
	v_pk_mul_f32 v[78:79], v[78:79], v[80:81] op_sel_hi:[1,0]
	v_pk_mul_f32 v[76:77], v[76:77], v[80:81] op_sel_hi:[1,0]
	v_pk_mul_f32 v[84:85], v[74:75], v[80:81] op_sel_hi:[1,0]
	v_pk_mul_f32 v[74:75], v[72:73], v[80:81] op_sel_hi:[1,0]
	v_cvt_pk_bf16_f32 v72, v76, v77
	v_cvt_pk_bf16_f32 v73, v78, v79
	v_pk_mul_f32 v[70:71], v[70:71], v[80:81] op_sel_hi:[1,0]
	v_cvt_pk_bf16_f32 v74, v74, v75
	v_cvt_pk_bf16_f32 v75, v84, v85
	ds_bpermute_b32 v208, v230, v72
	ds_bpermute_b32 v209, v230, v73
	ds_bpermute_b32 v210, v230, v74
	ds_bpermute_b32 v211, v230, v75
	v_pk_mul_f32 v[68:69], v[68:69], v[80:81] op_sel_hi:[1,0]
	s_nop 0
	v_pk_mul_f32 v[72:73], v[66:67], v[80:81] op_sel_hi:[1,0]
	v_pk_mul_f32 v[66:67], v[64:65], v[80:81] op_sel_hi:[1,0]
	v_add_u32_e32 v80, 0x80, v154
	v_cvt_pk_bf16_f32 v64, v68, v69
	v_cvt_pk_bf16_f32 v65, v70, v71
	v_ashrrev_i32_e32 v81, 31, v80
	v_cvt_pk_bf16_f32 v66, v66, v67
	v_cvt_pk_bf16_f32 v67, v72, v73
	ds_bpermute_b32 v212, v230, v64
	ds_bpermute_b32 v213, v230, v65
	ds_bpermute_b32 v214, v230, v66
	ds_bpermute_b32 v215, v230, v67
	s_waitcnt lgkmcnt(4)
; __device__ __forceinline__ unsigned cvt_pk_bf16(float lo, float hi) { unsigned r; asm volatile("v_cvt_pk_bf16_f32 %0, %1, %2" : "=v"(r) : "v"(lo), "v"(hi)); return r; }
; #define PG8_BAR __builtin_amdgcn_s_barrier()
;     __device__ __forceinline__ void operator()(const f32x4 (&acc)[2][2][4][2], const Unit& u, int wr, int wc, int fr, int fq) const {
;     ...
;                 bf16_t* rowp = O + (size_t)row * ldc + col0;
; #pragma unroll
;                 for (int bj = 0; bj < 2; ++bj) {
;                     f32x4 v0 = acc[ai][bj][m][0] * rs, v1 = acc[ai][bj][m][1] * rs;
;                     if (ACT == 1) {
; #pragma unroll
;                         for (int e = 0; e < 4; ++e) { float a = fmaxf(v0[e], 0.f); v0[e] = a * a; float b = fmaxf(v1[e], 0.f); v1[e] = b * b; }
;                     }
;                     u32x4 w; w.x = cvt_pk_bf16(v0[0], v0[1]); w.y = cvt_pk_bf16(v0[2], v0[3]); w.z = cvt_pk_bf16(v1[0], v1[1]); w.w = cvt_pk_bf16(v1[2], v1[3]);
;                     *(u32x4*)(rowp + bj * HALF) = w;
; template <class Epi, class Sched, bool ALIGN_EPI = false, bool SP2 = false>
; __device__ __forceinline__ void gemm_phase(PG8_LAS unsigned char* lds, const Gemm g, const Sched& S, const Epi& E) {
;     ...
;         cur = nxt; cA = nA; cB = nB; ++ui;
;         if constexpr (ALIGN_EPI) { if (wr == 1) PG8_BAR; }
	global_store_dwordx4 v[82:83], v[208:211], off
	s_waitcnt lgkmcnt(0)
	global_store_dwordx4 v[82:83], v[212:215], off offset:256
	s_nop 1
	v_mad_i64_i32 v[66:67], s[24:25], v80, s49, 0
	v_lshl_add_u64 v[66:67], v[66:67], 1, s[78:79]
	v_lshl_add_u64 v[66:67], v[66:67], 0, v[152:153]
	v_mov_b32_e32 v64, v196
	v_pk_mul_f32 v[62:63], v[62:63], v[64:65] op_sel_hi:[1,0]
	v_pk_mul_f32 v[60:61], v[60:61], v[64:65] op_sel_hi:[1,0]
	v_pk_mul_f32 v[68:69], v[58:59], v[64:65] op_sel_hi:[1,0]
	v_pk_mul_f32 v[58:59], v[56:57], v[64:65] op_sel_hi:[1,0]
	v_cvt_pk_bf16_f32 v56, v60, v61
	v_cvt_pk_bf16_f32 v57, v62, v63
	v_pk_mul_f32 v[54:55], v[54:55], v[64:65] op_sel_hi:[1,0]
	v_cvt_pk_bf16_f32 v58, v58, v59
	v_cvt_pk_bf16_f32 v59, v68, v69
	ds_bpermute_b32 v208, v230, v56
	ds_bpermute_b32 v209, v230, v57
	ds_bpermute_b32 v210, v230, v58
	ds_bpermute_b32 v211, v230, v59
	v_pk_mul_f32 v[52:53], v[52:53], v[64:65] op_sel_hi:[1,0]
	s_nop 0
	v_pk_mul_f32 v[56:57], v[50:51], v[64:65] op_sel_hi:[1,0]
	v_pk_mul_f32 v[50:51], v[48:49], v[64:65] op_sel_hi:[1,0]
	v_add_u32_e32 v64, 0x90, v154
	v_cvt_pk_bf16_f32 v48, v52, v53
	v_cvt_pk_bf16_f32 v49, v54, v55
	v_ashrrev_i32_e32 v65, 31, v64
	v_cvt_pk_bf16_f32 v50, v50, v51
	v_cvt_pk_bf16_f32 v51, v56, v57
	ds_bpermute_b32 v212, v230, v48
	ds_bpermute_b32 v213, v230, v49
	ds_bpermute_b32 v214, v230, v50
	ds_bpermute_b32 v215, v230, v51
	s_waitcnt lgkmcnt(4)
	global_store_dwordx4 v[66:67], v[208:211], off
	s_waitcnt lgkmcnt(0)
	global_store_dwordx4 v[66:67], v[212:215], off offset:256
	s_nop 1
	v_mad_i64_i32 v[50:51], s[24:25], v64, s49, 0
	v_lshl_add_u64 v[50:51], v[50:51], 1, s[78:79]
	v_lshl_add_u64 v[50:51], v[50:51], 0, v[152:153]
	v_mov_b32_e32 v48, v200
	v_pk_mul_f32 v[46:47], v[46:47], v[48:49] op_sel_hi:[1,0]
	v_pk_mul_f32 v[44:45], v[44:45], v[48:49] op_sel_hi:[1,0]
	v_pk_mul_f32 v[52:53], v[42:43], v[48:49] op_sel_hi:[1,0]
	v_pk_mul_f32 v[42:43], v[40:41], v[48:49] op_sel_hi:[1,0]
	v_cvt_pk_bf16_f32 v40, v44, v45
	v_cvt_pk_bf16_f32 v41, v46, v47
	v_pk_mul_f32 v[38:39], v[38:39], v[48:49] op_sel_hi:[1,0]
	v_cvt_pk_bf16_f32 v42, v42, v43
	v_cvt_pk_bf16_f32 v43, v52, v53
	ds_bpermute_b32 v208, v230, v40
	ds_bpermute_b32 v209, v230, v41
	ds_bpermute_b32 v210, v230, v42
	ds_bpermute_b32 v211, v230, v43
	v_pk_mul_f32 v[36:37], v[36:37], v[48:49] op_sel_hi:[1,0]
	s_nop 0
	v_pk_mul_f32 v[40:41], v[34:35], v[48:49] op_sel_hi:[1,0]
	v_pk_mul_f32 v[34:35], v[32:33], v[48:49] op_sel_hi:[1,0]
	v_add_u32_e32 v48, 0xa0, v154
	v_cvt_pk_bf16_f32 v32, v36, v37
	v_cvt_pk_bf16_f32 v33, v38, v39
	v_ashrrev_i32_e32 v49, 31, v48
	v_cvt_pk_bf16_f32 v34, v34, v35
	v_cvt_pk_bf16_f32 v35, v40, v41
	ds_bpermute_b32 v212, v230, v32
	ds_bpermute_b32 v213, v230, v33
	ds_bpermute_b32 v214, v230, v34
	ds_bpermute_b32 v215, v230, v35
	s_waitcnt lgkmcnt(4)
	global_store_dwordx4 v[50:51], v[208:211], off
	s_waitcnt lgkmcnt(0)
	global_store_dwordx4 v[50:51], v[212:215], off offset:256
	s_nop 1
	v_mad_i64_i32 v[34:35], s[24:25], v48, s49, 0
	v_lshl_add_u64 v[34:35], v[34:35], 1, s[78:79]
	v_lshl_add_u64 v[34:35], v[34:35], 0, v[152:153]
	v_mov_b32_e32 v32, v216
	v_pk_mul_f32 v[30:31], v[30:31], v[32:33] op_sel_hi:[1,0]
	v_pk_mul_f32 v[28:29], v[28:29], v[32:33] op_sel_hi:[1,0]
	v_pk_mul_f32 v[36:37], v[26:27], v[32:33] op_sel_hi:[1,0]
	v_pk_mul_f32 v[26:27], v[24:25], v[32:33] op_sel_hi:[1,0]
	v_cvt_pk_bf16_f32 v24, v28, v29
	v_cvt_pk_bf16_f32 v25, v30, v31
	v_pk_mul_f32 v[22:23], v[22:23], v[32:33] op_sel_hi:[1,0]
	v_cvt_pk_bf16_f32 v26, v26, v27
	v_cvt_pk_bf16_f32 v27, v36, v37
	ds_bpermute_b32 v208, v230, v24
	ds_bpermute_b32 v209, v230, v25
	ds_bpermute_b32 v210, v230, v26
	ds_bpermute_b32 v211, v230, v27
	v_pk_mul_f32 v[20:21], v[20:21], v[32:33] op_sel_hi:[1,0]
	s_nop 0
	v_pk_mul_f32 v[24:25], v[18:19], v[32:33] op_sel_hi:[1,0]
	v_pk_mul_f32 v[18:19], v[16:17], v[32:33] op_sel_hi:[1,0]
	v_add_u32_e32 v32, 0xb0, v154
	v_cvt_pk_bf16_f32 v16, v20, v21
	v_cvt_pk_bf16_f32 v17, v22, v23
	v_ashrrev_i32_e32 v33, 31, v32
	v_cvt_pk_bf16_f32 v18, v18, v19
	v_cvt_pk_bf16_f32 v19, v24, v25
	ds_bpermute_b32 v212, v230, v16
	ds_bpermute_b32 v213, v230, v17
	ds_bpermute_b32 v214, v230, v18
	ds_bpermute_b32 v215, v230, v19
	s_waitcnt lgkmcnt(4)
	global_store_dwordx4 v[34:35], v[208:211], off
	s_waitcnt lgkmcnt(0)
	global_store_dwordx4 v[34:35], v[212:215], off offset:256
	s_nop 1
	v_mad_i64_i32 v[18:19], s[24:25], v32, s49, 0
	v_lshl_add_u64 v[18:19], v[18:19], 1, s[78:79]
	v_lshl_add_u64 v[18:19], v[18:19], 0, v[152:153]
	s_mov_b64 s[24:25], -1
	v_mov_b32_e32 v16, v220
	v_pk_mul_f32 v[14:15], v[14:15], v[16:17] op_sel_hi:[1,0]
	v_pk_mul_f32 v[12:13], v[12:13], v[16:17] op_sel_hi:[1,0]
	v_pk_mul_f32 v[20:21], v[10:11], v[16:17] op_sel_hi:[1,0]
	v_pk_mul_f32 v[10:11], v[8:9], v[16:17] op_sel_hi:[1,0]
	v_cvt_pk_bf16_f32 v8, v12, v13
	v_cvt_pk_bf16_f32 v9, v14, v15
	s_andn2_b64 vcc, exec, s[36:37]
	v_cvt_pk_bf16_f32 v10, v10, v11
	v_cvt_pk_bf16_f32 v11, v20, v21
	ds_bpermute_b32 v208, v230, v8
	ds_bpermute_b32 v209, v230, v9
	ds_bpermute_b32 v210, v230, v10
	ds_bpermute_b32 v211, v230, v11
	v_pk_mul_f32 v[6:7], v[6:7], v[16:17] op_sel_hi:[1,0]
	v_pk_mul_f32 v[4:5], v[4:5], v[16:17] op_sel_hi:[1,0]
	v_pk_mul_f32 v[8:9], v[2:3], v[16:17] op_sel_hi:[1,0]
	v_pk_mul_f32 v[2:3], v[0:1], v[16:17] op_sel_hi:[1,0]
	v_cvt_pk_bf16_f32 v0, v4, v5
	v_cvt_pk_bf16_f32 v1, v6, v7
	s_nop 0
	v_cvt_pk_bf16_f32 v2, v2, v3
	v_cvt_pk_bf16_f32 v3, v8, v9
	ds_bpermute_b32 v212, v230, v0
	ds_bpermute_b32 v213, v230, v1
	ds_bpermute_b32 v214, v230, v2
	ds_bpermute_b32 v215, v230, v3
	s_waitcnt lgkmcnt(4)
	global_store_dwordx4 v[18:19], v[208:211], off
	s_waitcnt lgkmcnt(0)
	global_store_dwordx4 v[18:19], v[212:215], off offset:256
	s_cbranch_vccnz .LBB0_422
	v_readlane_b32 s24, v250, 34
	v_readlane_b32 s25, v250, 35
	s_andn2_b64 vcc, exec, s[24:25]
	s_setprio 1
	s_cbranch_vccnz .LBB0_421
	s_setprio 0
	s_barrier
	s_branch .LBB0_421

; #define PG8_STAGE(bufoff, gbase, voff) do { _Pragma("unroll") for (int _i = 0; _i < 2; ++_i) \
;         __builtin_amdgcn_global_load_lds((const unsigned*)((const char*)(gbase) + (voff)[_i]), (PG8_LAS unsigned*)(lds + (bufoff) + ldsw + _i * 8192), 16, 0, 0); } while (0)
; #define PG8_BAR __builtin_amdgcn_s_barrier()
; template <class Epi, class Sched, bool ALIGN_EPI = false, bool SP2 = false>
; __device__ __forceinline__ void gemm_phase(PG8_LAS unsigned char* lds, const Gemm g, const Sched& S, const Epi& E) {
;     ...
;     for (int i = 0; i < 2; ++i) { int R, C; stage_rc(tid * 16 + i * 8192, R, C); const int Rb = Epi::PERM ? ((R & ~31) + perm32(R & 31)) : R;
;         voffA[i] = (unsigned)(R * K + C) * 2u; voffB[i] = (unsigned)(Rb * K + C) * 2u; }
;     const size_t kstep = (size_t)(BK * 2);
;     const size_t hstep = (size_t)HALF * K * 2;
;     const size_t tstep = 2 * hstep;
;     const unsigned ldsw = (unsigned)wid * 1024u;
;     const int aoff = lds_byte(wr * 64 + fr, fq * 8), boff = lds_byte(wc * 32 + fr, fq * 8);
;     ...
;     const char* cA = (const char*)g.A + (size_t)cur.pm * tstep; const char* cB = (const char*)g.Bt + (size_t)cur.pn * tstep;
;     S.a_ready(cur);
;     if constexpr (SP2) {
;         PG8_STAGE(PG8_SB(0, 0), cB, voffB); PG8_STAGE(PG8_SB(0, 1), cB + hstep, voffB); PG8_STAGE(PG8_SA(0, 0), cA, voffA); PG8_STAGE(PG8_SA(0, 1), cA + hstep, voffA);
;         if (wr == 1) PG8_BAR;
.LBB0_1045:
	s_andn2_b64 vcc, exec, s[0:1]
	v_readlane_b32 s0, v251, 26
	v_readlane_b32 s1, v251, 27
	s_nop 1
	v_cndmask_b32_e64 v0, 0, 1, s[0:1]
	v_cmp_ne_u32_e64 s[48:49], 1, v0
	s_cbranch_vccnz .LBB0_1136
	v_mov_b32_e32 v6, v204
	s_waitcnt lgkmcnt(0)
	s_barrier
	s_and_b64 vcc, exec, s[48:49]
	v_readfirstlane_b32 s22, v6
	s_cbranch_vccnz .LBB0_1082
	v_lshlrev_b32_e32 v3, 4, v6
	v_add_u32_e32 v1, 0x2000, v3
	v_ashrrev_i32_e32 v0, 31, v1
	v_lshrrev_b32_e32 v0, 22, v0
	v_add_u32_e32 v0, v1, v0
	v_ashrrev_i32_e32 v0, 10, v0
	v_mul_i32_i24_e32 v2, 0x400, v0
	v_sub_u32_e32 v1, v1, v2
	v_lshrrev_b32_e32 v2, 4, v1
	v_bitop3_b32 v2, v2, v1, 32 bitop3:0x6c
	v_ashrrev_i32_e32 v1, 31, v2
	v_lshrrev_b32_e32 v1, 26, v1
	v_add_u32_e32 v4, v2, v1
	v_lshlrev_b32_e32 v5, 3, v0
	s_lshl_b32 s0, s45, 21
	v_readlane_b32 s1, v251, 24
	v_ashrrev_i32_e32 v1, 6, v4
	v_and_b32_e32 v5, -16, v5
	s_add_u32 s58, s1, s0
	v_readlane_b32 s0, v251, 25
	v_add_u32_e32 v5, v1, v5
	s_addc_u32 s59, s0, 0
	v_and_b32_e32 v7, 3, v1
	s_mov_b32 s0, 0x1fffe0
	v_lshrrev_b32_e32 v8, 2, v5
	v_lshlrev_b32_e32 v9, 1, v5
	v_and_b32_e32 v4, 0xc0, v4
	v_and_or_b32 v7, v5, s0, v7
	v_and_b32_e32 v8, 4, v8
	v_and_b32_e32 v9, 24, v9
	v_sub_u32_e32 v2, v2, v4
	v_or3_b32 v7, v7, v8, v9
	v_lshlrev_b32_e32 v8, 5, v0
	v_ashrrev_i16_sdwa v2, v205, sext(v2) dst_sel:DWORD dst_unused:UNUSED_PAD src0_sel:DWORD src1_sel:BYTE_0
	v_and_b32_e32 v8, 32, v8
	v_bfe_i32 v2, v2, 0, 16
	v_add_lshl_u32 v4, v8, v2, 1
	v_lshl_add_u32 v128, v7, 11, v4
	v_lshl_add_u32 v130, v5, 11, v4
	v_bfe_i32 v4, v6, 27, 1
	v_lshrrev_b32_e32 v4, 22, v4
	v_add_u32_e32 v4, v3, v4
	v_and_b32_e32 v4, 0xfffffc00, v4
	v_sub_u32_e32 v3, v3, v4
	v_lshrrev_b32_e32 v4, 4, v3
	v_bitop3_b32 v5, v4, v3, 32 bitop3:0x6c
	v_ashrrev_i32_e32 v4, 31, v6
	v_lshrrev_b32_e32 v4, 26, v4
	v_ashrrev_i32_e32 v3, 31, v5
	v_add_u32_e32 v4, v6, v4
	v_lshrrev_b32_e32 v3, 26, v3
	v_ashrrev_i32_e32 v4, 6, v4
	v_add_u32_e32 v7, v5, v3
	v_lshlrev_b32_e32 v8, 3, v4
	v_ashrrev_i32_e32 v3, 6, v7
	v_and_b32_e32 v8, -16, v8
	v_add_u32_e32 v8, v3, v8
	v_and_b32_e32 v9, 3, v3
	v_lshrrev_b32_e32 v10, 2, v8
	v_lshlrev_b32_e32 v11, 1, v8
	v_and_b32_e32 v7, 0xc0, v7
	s_ashr_i32 s24, s22, 6
	v_and_or_b32 v9, v8, s0, v9
	v_and_b32_e32 v10, 4, v10
	v_and_b32_e32 v11, 24, v11
	v_sub_u32_e32 v5, v5, v7
	s_ashr_i32 s23, s22, 8
	s_lshl_b32 s60, s24, 10
	v_or3_b32 v9, v9, v10, v11
	v_lshlrev_b32_e32 v10, 5, v4
	v_ashrrev_i16_sdwa v5, v205, sext(v5) dst_sel:DWORD dst_unused:UNUSED_PAD src0_sel:DWORD src1_sel:BYTE_0
	v_readlane_b32 s0, v251, 48
	v_and_b32_e32 v10, 32, v10
	v_bfe_i32 v5, v5, 0, 16
	v_readlane_b32 s1, v251, 49
	s_add_u32 s26, s58, s0
	v_add_lshl_u32 v7, v10, v5, 1
	s_addc_u32 s27, s59, s1
	s_add_i32 s30, s60, 0
	v_lshl_add_u32 v138, v9, 11, v7
	s_add_i32 m0, s30, 0x10000
	v_lshl_add_u32 v132, v8, 11, v7
	global_load_lds_dwordx4 v138, s[26:27]
	s_add_i32 m0, s30, 0x12000
	s_add_u32 s0, s26, 0x40000
	global_load_lds_dwordx4 v128, s[26:27]
	s_addc_u32 s1, s27, 0
	s_add_i32 m0, s30, 0x14000
	s_add_i32 s61, s30, 0x2000
	global_load_lds_dwordx4 v138, s[0:1]
	s_add_i32 m0, s30, 0x16000
	s_add_i32 s74, s30, 0x4000
	global_load_lds_dwordx4 v128, s[0:1]
	v_readlane_b32 s0, v251, 50
	s_mov_b32 m0, s30
	v_readlane_b32 s1, v251, 51
	s_add_i32 s75, s30, 0x6000
	s_cmp_eq_u32 s23, 1
	v_writelane_b32 v250, s48, 32
	s_nop 1
	global_load_lds_dwordx4 v132, s[0:1]
	s_mov_b32 m0, s61
	v_writelane_b32 v250, s49, 33
	global_load_lds_dwordx4 v130, s[0:1]
	v_readlane_b32 s0, v251, 52
	s_mov_b32 m0, s74
	v_readlane_b32 s1, v251, 53
	s_nop 4
	global_load_lds_dwordx4 v132, s[0:1]
	s_mov_b32 m0, s75
	s_nop 0
	global_load_lds_dwordx4 v130, s[0:1]
	s_cselect_b64 s[0:1], -1, 0
	s_cmp_lg_u32 s23, 1
	s_setprio 1
	s_cbranch_scc1 .LBB0_1049
	s_setprio 0
	s_barrier

; #define PG8_BAR __builtin_amdgcn_s_barrier()
; template <class Epi, class Sched, bool ALIGN_EPI = false, bool SP2 = false>
; __device__ __forceinline__ void gemm_phase(PG8_LAS unsigned char* lds, const Gemm g, const Sched& S, const Epi& E) {
;     ...
;         if (!has_next) break;
; #pragma unroll
;         for (int a = 0; a < 2; ++a)
; #pragma unroll
;             for (int b = 0; b < 2; ++b)
; #pragma unroll
;                 for (int m = 0; m < 4; ++m)
; #pragma unroll
;                     for (int n = 0; n < 2; ++n) acc[a][b][m][n] = (f32x4){0.f, 0.f, 0.f, 0.f};
;         cur = nxt; cA = nA; cB = nB; ++ui;
;         if constexpr (ALIGN_EPI) { if (wr == 1) PG8_BAR; }
.LBB0_1078:
	s_or_b64 exec, exec, s[24:25]
	s_andn2_b64 vcc, exec, s[40:41]
	s_mov_b64 s[24:25], -1
	s_cbranch_vccnz .LBB0_1051
	s_andn2_b64 vcc, exec, s[0:1]
	s_setprio 1
	s_cbranch_vccnz .LBB0_1050
	s_setprio 0
	s_barrier
	s_branch .LBB0_1050

; #define PG8_STAGE(bufoff, gbase, voff) do { _Pragma("unroll") for (int _i = 0; _i < 2; ++_i) \
;         __builtin_amdgcn_global_load_lds((const unsigned*)((const char*)(gbase) + (voff)[_i]), (PG8_LAS unsigned*)(lds + (bufoff) + ldsw + _i * 8192), 16, 0, 0); } while (0)
; #define PG8_BAR __builtin_amdgcn_s_barrier()
; template <class Epi, class Sched, bool ALIGN_EPI = false, bool SP2 = false>
; __device__ __forceinline__ void gemm_phase(PG8_LAS unsigned char* lds, const Gemm g, const Sched& S, const Epi& E) {
;     ...
;     for (int i = 0; i < 2; ++i) { int R, C; stage_rc(tid * 16 + i * 8192, R, C); const int Rb = Epi::PERM ? ((R & ~31) + perm32(R & 31)) : R;
;         voffA[i] = (unsigned)(R * K + C) * 2u; voffB[i] = (unsigned)(Rb * K + C) * 2u; }
;     const size_t kstep = (size_t)(BK * 2);
;     const size_t hstep = (size_t)HALF * K * 2;
;     const size_t tstep = 2 * hstep;
;     const unsigned ldsw = (unsigned)wid * 1024u;
;     const int aoff = lds_byte(wr * 64 + fr, fq * 8), boff = lds_byte(wc * 32 + fr, fq * 8);
;     ...
;     const char* cA = (const char*)g.A + (size_t)cur.pm * tstep; const char* cB = (const char*)g.Bt + (size_t)cur.pn * tstep;
;     S.a_ready(cur);
;     if constexpr (SP2) {
;         PG8_STAGE(PG8_SB(0, 0), cB, voffB); PG8_STAGE(PG8_SB(0, 1), cB + hstep, voffB); PG8_STAGE(PG8_SA(0, 0), cA, voffA); PG8_STAGE(PG8_SA(0, 1), cA + hstep, voffA);
;         if (wr == 1) PG8_BAR;
.LBB0_1138:
	s_andn2_b64 vcc, exec, s[0:1]
	s_cbranch_vccnz .LBB0_1213
	v_readlane_b32 s0, v251, 30
	v_mov_b32_e32 v6, v204
	v_readlane_b32 s1, v251, 31
	s_andn2_b64 vcc, exec, s[0:1]
	v_readfirstlane_b32 s22, v6
	s_cbranch_vccnz .LBB0_1159
	s_waitcnt lgkmcnt(1)
	v_lshlrev_b32_e32 v3, 4, v6
	s_waitcnt lgkmcnt(0)
	v_add_u32_e32 v1, 0x2000, v3
	v_ashrrev_i32_e32 v0, 31, v1
	v_lshrrev_b32_e32 v0, 22, v0
	v_add_u32_e32 v0, v1, v0
	v_ashrrev_i32_e32 v0, 10, v0
	v_mul_i32_i24_e32 v2, 0x400, v0
	v_sub_u32_e32 v1, v1, v2
	v_lshrrev_b32_e32 v2, 4, v1
	v_bitop3_b32 v2, v2, v1, 32 bitop3:0x6c
	v_ashrrev_i32_e32 v1, 31, v2
	v_lshrrev_b32_e32 v1, 26, v1
	v_add_u32_e32 v4, v2, v1
	v_lshlrev_b32_e32 v5, 3, v0
	s_lshl_b32 s0, s45, 23
	v_readlane_b32 s1, v251, 28
	v_ashrrev_i32_e32 v1, 6, v4
	v_and_b32_e32 v5, -16, v5
	s_add_u32 s46, s1, s0
	v_readlane_b32 s0, v251, 29
	v_add_u32_e32 v5, v1, v5
	s_addc_u32 s47, s0, 0
	v_and_b32_e32 v7, 3, v1
	s_mov_b32 s0, 0x1fffe0
	v_lshrrev_b32_e32 v8, 2, v5
	v_lshlrev_b32_e32 v9, 1, v5
	v_and_b32_e32 v4, 0xc0, v4
	v_and_or_b32 v7, v5, s0, v7
	v_and_b32_e32 v8, 4, v8
	v_and_b32_e32 v9, 24, v9
	v_sub_u32_e32 v2, v2, v4
	v_or3_b32 v7, v7, v8, v9
	v_lshlrev_b32_e32 v8, 5, v0
	v_ashrrev_i16_sdwa v2, v205, sext(v2) dst_sel:DWORD dst_unused:UNUSED_PAD src0_sel:DWORD src1_sel:BYTE_0
	v_and_b32_e32 v8, 32, v8
	v_bfe_i32 v2, v2, 0, 16
	v_add_lshl_u32 v4, v8, v2, 1
	v_lshl_add_u32 v128, v7, 11, v4
	v_lshl_add_u32 v130, v5, 11, v4
	v_bfe_i32 v4, v6, 27, 1
	v_lshrrev_b32_e32 v4, 22, v4
	v_add_u32_e32 v4, v3, v4
	v_and_b32_e32 v4, 0xfffffc00, v4
	v_sub_u32_e32 v3, v3, v4
	v_lshrrev_b32_e32 v4, 4, v3
	v_bitop3_b32 v5, v4, v3, 32 bitop3:0x6c
	v_ashrrev_i32_e32 v4, 31, v6
	v_lshrrev_b32_e32 v4, 26, v4
	v_ashrrev_i32_e32 v3, 31, v5
	v_add_u32_e32 v4, v6, v4
	v_lshrrev_b32_e32 v3, 26, v3
	v_ashrrev_i32_e32 v4, 6, v4
	v_add_u32_e32 v7, v5, v3
	v_lshlrev_b32_e32 v8, 3, v4
	v_ashrrev_i32_e32 v3, 6, v7
	v_and_b32_e32 v8, -16, v8
	v_add_u32_e32 v8, v3, v8
	v_and_b32_e32 v9, 3, v3
	v_lshrrev_b32_e32 v10, 2, v8
	v_lshlrev_b32_e32 v11, 1, v8
	v_and_b32_e32 v7, 0xc0, v7
	v_writelane_b32 v250, s48, 32
	s_ashr_i32 s23, s22, 6
	v_and_or_b32 v9, v8, s0, v9
	v_and_b32_e32 v10, 4, v10
	v_and_b32_e32 v11, 24, v11
	v_sub_u32_e32 v5, v5, v7
	v_writelane_b32 v250, s49, 33
	s_ashr_i32 s24, s22, 8
	s_lshl_b32 s48, s23, 10
	v_or3_b32 v9, v9, v10, v11
	v_lshlrev_b32_e32 v10, 5, v4
	v_ashrrev_i16_sdwa v5, v205, sext(v5) dst_sel:DWORD dst_unused:UNUSED_PAD src0_sel:DWORD src1_sel:BYTE_0
	v_readlane_b32 s0, v251, 39
	v_and_b32_e32 v10, 32, v10
	v_bfe_i32 v5, v5, 0, 16
	v_readlane_b32 s1, v251, 40
	s_add_u32 s26, s46, s0
	v_add_lshl_u32 v7, v10, v5, 1
	s_addc_u32 s27, s47, s1
	s_add_i32 s49, s48, 0
	v_lshl_add_u32 v138, v9, 11, v7
	s_add_i32 m0, s49, 0x10000
	v_lshl_add_u32 v132, v8, 11, v7
	global_load_lds_dwordx4 v138, s[26:27]
	s_add_i32 m0, s49, 0x12000
	s_add_u32 s0, s26, 0x40000
	global_load_lds_dwordx4 v128, s[26:27]
	s_addc_u32 s1, s27, 0
	s_add_i32 m0, s49, 0x14000
	s_add_i32 s52, s49, 0x2000
	global_load_lds_dwordx4 v138, s[0:1]
	s_add_i32 m0, s49, 0x16000
	s_add_i32 s53, s49, 0x4000
	global_load_lds_dwordx4 v128, s[0:1]
	v_readlane_b32 s0, v251, 44
	s_mov_b32 m0, s49
	v_readlane_b32 s1, v251, 45
	s_add_i32 s54, s49, 0x6000
	s_cmp_eq_u32 s24, 1
	v_writelane_b32 v250, s95, 34
	s_nop 1
	global_load_lds_dwordx4 v132, s[0:1]
	s_mov_b32 m0, s52
	s_nop 0
	global_load_lds_dwordx4 v130, s[0:1]
	v_readlane_b32 s0, v251, 46
	s_mov_b32 m0, s53
	v_readlane_b32 s1, v251, 47
	s_nop 4
	global_load_lds_dwordx4 v132, s[0:1]
	s_mov_b32 m0, s54
	s_nop 0
	global_load_lds_dwordx4 v130, s[0:1]
	s_cselect_b64 s[0:1], -1, 0
	s_cmp_lg_u32 s24, 1
	s_setprio 1
	s_cbranch_scc1 .LBB0_1142
	s_setprio 0
	s_barrier

; __device__ __forceinline__ unsigned cvt_pk_bf16(float lo, float hi) { unsigned r; asm volatile("v_cvt_pk_bf16_f32 %0, %1, %2" : "=v"(r) : "v"(lo), "v"(hi)); return r; }
;     __device__ __forceinline__ void operator()(const f32x4 (&acc)[2][2][4][2], const Unit& u, int wr, int wc, int fr, int fq) const {
;         const int row0 = u.pm * BM + wr * 64 + fr, col0 = u.pn * BM + wc * 32 + 8 * fq;
; #pragma unroll
;         for (int ai = 0; ai < 2; ++ai)
; #pragma unroll
;             for (int m = 0; m < 4; ++m) {
;                 const int row = row0 + ai * HALF + m * 16;
;                 const f32x4* sp = (const f32x4*)(ss + (size_t)row * 16);
;                 const f32x4 a0 = sp[0], a1 = sp[1], a2 = sp[2], a3 = sp[3];
;                 const float tot = ((a0.x + a0.y) + (a0.z + a0.w)) + ((a1.x + a1.y) + (a1.z + a1.w)) + ((a2.x + a2.y) + (a2.z + a2.w)) + ((a3.x + a3.y) + (a3.z + a3.w));
;                 const float rs = rsqrtf(tot * (1.0f / 1024.0f) + 1e-6f);
;                 bf16_t* rowp = O + (size_t)row * ldc + col0;
; #pragma unroll
;                 for (int bj = 0; bj < 2; ++bj) {
;                     f32x4 v0 = acc[ai][bj][m][0] * rs, v1 = acc[ai][bj][m][1] * rs;
;                     if (ACT == 1) {
; #pragma unroll
;                         for (int e = 0; e < 4; ++e) { float a = fmaxf(v0[e], 0.f); v0[e] = a * a; float b = fmaxf(v1[e], 0.f); v1[e] = b * b; }
;                     }
;                     u32x4 w; w.x = cvt_pk_bf16(v0[0], v0[1]); w.y = cvt_pk_bf16(v0[2], v0[3]); w.z = cvt_pk_bf16(v1[0], v1[1]); w.w = cvt_pk_bf16(v1[2], v1[3]);
;                     *(u32x4*)(rowp + bj * HALF) = w;
.LBB0_1155:
	s_setprio 0
	v_lshl_add_u32 v152, s88, 8, v154
	v_ashrrev_i32_e32 v153, 31, v152
	v_lshlrev_b64 v[176:177], 6, v[152:153]
	v_and_or_b32 v176, v204, 48, v176
	v_lshl_add_u64 v[176:177], s[90:91], 0, v[176:177]
	v_mov_b32_e32 v178, 0x2000
	v_mov_b32_e32 v179, 0
	v_lshl_add_u64 v[178:179], v[176:177], 0, v[178:179]
	global_load_dwordx4 v[196:199], v[178:179], off
	global_load_dwordx4 v[208:211], v[178:179], off offset:1024
	global_load_dwordx4 v[212:215], v[178:179], off offset:2048
	global_load_dwordx4 v[216:219], v[178:179], off offset:3072
	v_bfe_u32 v228, v204, 2, 4
	v_and_b32_e32 v229, -16, v154
	v_or_b32_e32 v229, v229, v228
	v_lshl_add_u32 v152, s88, 8, v229
	v_ashrrev_i32_e32 v153, 31, v152
	v_and_b32_e32 v229, 3, v204
	v_lshlrev_b32_e32 v230, 3, v229
	v_and_b32_e32 v231, -32, v156
	v_or_b32_e32 v230, v230, v231
	v_lshl_add_u32 v228, v229, 4, v228
	v_lshlrev_b32_e32 v228, 2, v228
	v_lshl_or_b32 v150, s30, 8, v230
	v_ashrrev_i32_e32 v151, 31, v150
	v_lshlrev_b64 v[150:151], 1, v[150:151]
	s_mov_b64 s[24:25], -1
	v_lshlrev_b64 v[160:161], 13, v[152:153]
	v_lshl_add_u64 v[160:161], s[78:79], 0, v[160:161]
	v_lshl_add_u64 v[160:161], v[160:161], 0, v[150:151]
	s_waitcnt vmcnt(10)
	v_mov_b32_e32 v180, v232
	v_mov_b32_e32 v181, v233
	v_mov_b32_e32 v182, v234
	v_mov_b32_e32 v183, v235
	v_mov_b32_e32 v184, v236
	v_mov_b32_e32 v185, v237
	v_mov_b32_e32 v186, v238
	v_mov_b32_e32 v187, v239
	v_mov_b32_e32 v188, v240
	v_mov_b32_e32 v189, v241
	v_mov_b32_e32 v190, v242
	v_mov_b32_e32 v191, v243
	v_mov_b32_e32 v192, v244
	v_mov_b32_e32 v193, v245
	v_mov_b32_e32 v194, v246
	v_mov_b32_e32 v195, v247
	v_add_f32_e32 v180, v180, v181
	v_add_f32_e32 v182, v182, v183
	v_add_f32_e32 v184, v184, v185
	v_add_f32_e32 v186, v186, v187
	v_add_f32_e32 v188, v188, v189
	v_add_f32_e32 v190, v190, v191
	v_add_f32_e32 v192, v192, v193
	v_add_f32_e32 v194, v194, v195
	v_add_f32_e32 v180, v180, v182
	v_add_f32_e32 v184, v184, v186
	v_add_f32_e32 v188, v188, v190
	v_add_f32_e32 v192, v192, v194
	v_mov_b32_e32 v181, v180
	v_mov_b32_e32 v185, v184
	v_mov_b32_e32 v189, v188
	v_mov_b32_e32 v193, v192
	s_nop 1
	v_permlane16_swap_b32_e32 v180, v181
	v_permlane16_swap_b32_e32 v184, v185
	v_permlane16_swap_b32_e32 v188, v189
	v_permlane16_swap_b32_e32 v192, v193
	v_add_f32_e32 v180, v180, v181
	v_add_f32_e32 v184, v184, v185
	v_add_f32_e32 v188, v188, v189
	v_add_f32_e32 v192, v192, v193
	v_mov_b32_e32 v181, v180
	v_mov_b32_e32 v185, v184
	v_mov_b32_e32 v189, v188
	v_mov_b32_e32 v193, v192
	s_nop 1
	v_permlane32_swap_b32_e32 v180, v181
	v_permlane32_swap_b32_e32 v184, v185
	v_permlane32_swap_b32_e32 v188, v189
	v_permlane32_swap_b32_e32 v192, v193
	v_add_f32_e32 v180, v180, v181
	v_add_f32_e32 v184, v184, v185
	v_add_f32_e32 v188, v188, v189
	v_add_f32_e32 v192, v192, v193
	v_fmamk_f32 v180, v180, 0x3a800000, v137
	v_cmp_gt_f32_e32 vcc, s4, v180
	v_mul_f32_e32 v181, 0x4b800000, v180
	s_nop 0
	v_cndmask_b32_e32 v180, v180, v181, vcc
	v_rsq_f32_e32 v180, v180
	s_nop 0
	v_mul_f32_e32 v181, 0x45800000, v180
	v_cndmask_b32_e32 v180, v180, v181, vcc
	v_fmamk_f32 v184, v184, 0x3a800000, v137
	v_cmp_gt_f32_e32 vcc, s4, v184
	v_mul_f32_e32 v185, 0x4b800000, v184
	s_nop 0
	v_cndmask_b32_e32 v184, v184, v185, vcc
	v_rsq_f32_e32 v184, v184
	s_nop 0
	v_mul_f32_e32 v185, 0x45800000, v184
	v_cndmask_b32_e32 v184, v184, v185, vcc
	v_fmamk_f32 v188, v188, 0x3a800000, v137
	v_cmp_gt_f32_e32 vcc, s4, v188
	v_mul_f32_e32 v189, 0x4b800000, v188
	s_nop 0
	v_cndmask_b32_e32 v188, v188, v189, vcc
	v_rsq_f32_e32 v188, v188
	s_nop 0
	v_mul_f32_e32 v189, 0x45800000, v188
	v_cndmask_b32_e32 v188, v188, v189, vcc
	v_fmamk_f32 v192, v192, 0x3a800000, v137
	v_cmp_gt_f32_e32 vcc, s4, v192
	v_mul_f32_e32 v193, 0x4b800000, v192
	s_nop 0
	v_cndmask_b32_e32 v192, v192, v193, vcc
	v_rsq_f32_e32 v192, v192
	s_nop 0
	v_mul_f32_e32 v193, 0x45800000, v192
	v_cndmask_b32_e32 v192, v192, v193, vcc
	v_mov_b32_e32 v158, v180
	v_pk_mul_f32 v[120:121], v[120:121], v[158:159] op_sel_hi:[1,0]
	v_pk_mul_f32 v[124:125], v[124:125], v[158:159] op_sel_hi:[1,0]
	v_pk_mul_f32 v[122:123], v[122:123], v[158:159] op_sel_hi:[1,0]
	v_max_f32_e32 v120, 0, v120
	v_pk_mul_f32 v[126:127], v[126:127], v[158:159] op_sel_hi:[1,0]
	v_mul_f32_e32 v153, v120, v120
	v_max_f32_e32 v120, 0, v125
	v_max_f32_e32 v121, 0, v121
	v_max_f32_e32 v122, 0, v122
	v_max_f32_e32 v124, 0, v124
	v_mul_f32_e32 v120, v120, v120
	v_mul_f32_e32 v125, v121, v121
	v_max_f32_e32 v121, 0, v126
	v_mul_f32_e32 v126, v122, v122
	v_max_f32_e32 v122, 0, v127
	v_max_f32_e32 v123, 0, v123
	v_pk_mul_f32 v[112:113], v[112:113], v[158:159] op_sel_hi:[1,0]
	v_mul_f32_e32 v124, v124, v124
	v_mul_f32_e32 v121, v121, v121
	v_mul_f32_e32 v122, v122, v122
	v_mul_f32_e32 v123, v123, v123
	v_cvt_pk_bf16_f32 v120, v124, v120
	v_pk_mul_f32 v[116:117], v[116:117], v[158:159] op_sel_hi:[1,0]
	v_pk_mul_f32 v[114:115], v[114:115], v[158:159] op_sel_hi:[1,0]
	v_max_f32_e32 v112, 0, v112
	v_cvt_pk_bf16_f32 v121, v121, v122
	v_cvt_pk_bf16_f32 v122, v153, v125
	v_cvt_pk_bf16_f32 v123, v126, v123
	ds_bpermute_b32 v220, v228, v120
	ds_bpermute_b32 v221, v228, v121
	ds_bpermute_b32 v222, v228, v122
	ds_bpermute_b32 v223, v228, v123
	v_pk_mul_f32 v[118:119], v[118:119], v[158:159] op_sel_hi:[1,0]
	v_max_f32_e32 v113, 0, v113
	v_mul_f32_e32 v120, v112, v112
	v_max_f32_e32 v112, 0, v117
	v_max_f32_e32 v114, 0, v114
	v_max_f32_e32 v116, 0, v116
	v_mul_f32_e32 v112, v112, v112
	v_mul_f32_e32 v117, v113, v113
	v_max_f32_e32 v113, 0, v118
	v_mul_f32_e32 v118, v114, v114
	v_max_f32_e32 v114, 0, v119
	v_max_f32_e32 v115, 0, v115
	v_mul_f32_e32 v116, v116, v116
	v_mul_f32_e32 v113, v113, v113
	v_mul_f32_e32 v114, v114, v114
	v_mul_f32_e32 v115, v115, v115
	v_cvt_pk_bf16_f32 v112, v116, v112
	v_cvt_pk_bf16_f32 v113, v113, v114
	v_cvt_pk_bf16_f32 v114, v120, v117
	v_cvt_pk_bf16_f32 v115, v118, v115
	ds_bpermute_b32 v224, v228, v112
	ds_bpermute_b32 v225, v228, v113
	ds_bpermute_b32 v226, v228, v114
	ds_bpermute_b32 v227, v228, v115
	s_waitcnt lgkmcnt(4)
; __device__ __forceinline__ unsigned cvt_pk_bf16(float lo, float hi) { unsigned r; asm volatile("v_cvt_pk_bf16_f32 %0, %1, %2" : "=v"(r) : "v"(lo), "v"(hi)); return r; }
;     __device__ __forceinline__ void operator()(const f32x4 (&acc)[2][2][4][2], const Unit& u, int wr, int wc, int fr, int fq) const {
;     ...
;                 const int row = row0 + ai * HALF + m * 16;
;                 const f32x4* sp = (const f32x4*)(ss + (size_t)row * 16);
;                 const f32x4 a0 = sp[0], a1 = sp[1], a2 = sp[2], a3 = sp[3];
;                 const float tot = ((a0.x + a0.y) + (a0.z + a0.w)) + ((a1.x + a1.y) + (a1.z + a1.w)) + ((a2.x + a2.y) + (a2.z + a2.w)) + ((a3.x + a3.y) + (a3.z + a3.w));
;                 const float rs = rsqrtf(tot * (1.0f / 1024.0f) + 1e-6f);
;                 bf16_t* rowp = O + (size_t)row * ldc + col0;
; #pragma unroll
;                 for (int bj = 0; bj < 2; ++bj) {
;                     f32x4 v0 = acc[ai][bj][m][0] * rs, v1 = acc[ai][bj][m][1] * rs;
;                     if (ACT == 1) {
; #pragma unroll
;                         for (int e = 0; e < 4; ++e) { float a = fmaxf(v0[e], 0.f); v0[e] = a * a; float b = fmaxf(v1[e], 0.f); v1[e] = b * b; }
;                     }
;                     u32x4 w; w.x = cvt_pk_bf16(v0[0], v0[1]); w.y = cvt_pk_bf16(v0[2], v0[3]); w.z = cvt_pk_bf16(v1[0], v1[1]); w.w = cvt_pk_bf16(v1[2], v1[3]);
;                     *(u32x4*)(rowp + bj * HALF) = w;
	global_store_dwordx4 v[160:161], v[220:223], off
	s_waitcnt lgkmcnt(0)
	global_store_dwordx4 v[160:161], v[224:227], off offset:256
	s_nop 1
	v_or_b32_e32 v112, 16, v152
	v_ashrrev_i32_e32 v113, 31, v112
	v_lshlrev_b64 v[112:113], 13, v[112:113]
	v_lshl_add_u64 v[112:113], s[78:79], 0, v[112:113]
	v_lshl_add_u64 v[112:113], v[112:113], 0, v[150:151]
	v_mov_b32_e32 v114, v184
	v_pk_mul_f32 v[104:105], v[104:105], v[114:115] op_sel_hi:[1,0]
	v_pk_mul_f32 v[108:109], v[108:109], v[114:115] op_sel_hi:[1,0]
	v_pk_mul_f32 v[106:107], v[106:107], v[114:115] op_sel_hi:[1,0]
	v_max_f32_e32 v104, 0, v104
	v_pk_mul_f32 v[110:111], v[110:111], v[114:115] op_sel_hi:[1,0]
	v_mul_f32_e32 v115, v104, v104
	v_max_f32_e32 v104, 0, v109
	v_max_f32_e32 v105, 0, v105
	v_max_f32_e32 v106, 0, v106
	v_max_f32_e32 v108, 0, v108
	v_mul_f32_e32 v104, v104, v104
	v_mul_f32_e32 v109, v105, v105
	v_max_f32_e32 v105, 0, v110
	v_mul_f32_e32 v110, v106, v106
	v_max_f32_e32 v106, 0, v111
	v_max_f32_e32 v107, 0, v107
	v_pk_mul_f32 v[96:97], v[96:97], v[114:115] op_sel_hi:[1,0]
	v_mul_f32_e32 v108, v108, v108
	v_mul_f32_e32 v105, v105, v105
	v_mul_f32_e32 v106, v106, v106
	v_mul_f32_e32 v107, v107, v107
	v_cvt_pk_bf16_f32 v104, v108, v104
	v_pk_mul_f32 v[100:101], v[100:101], v[114:115] op_sel_hi:[1,0]
	v_pk_mul_f32 v[98:99], v[98:99], v[114:115] op_sel_hi:[1,0]
	v_max_f32_e32 v96, 0, v96
	v_cvt_pk_bf16_f32 v105, v105, v106
	v_cvt_pk_bf16_f32 v106, v115, v109
	v_cvt_pk_bf16_f32 v107, v110, v107
	ds_bpermute_b32 v220, v228, v104
	ds_bpermute_b32 v221, v228, v105
	ds_bpermute_b32 v222, v228, v106
	ds_bpermute_b32 v223, v228, v107
	v_pk_mul_f32 v[102:103], v[102:103], v[114:115] op_sel_hi:[1,0]
	v_max_f32_e32 v97, 0, v97
	v_mul_f32_e32 v104, v96, v96
	v_max_f32_e32 v96, 0, v101
	v_max_f32_e32 v98, 0, v98
	v_max_f32_e32 v100, 0, v100
	v_mul_f32_e32 v96, v96, v96
	v_mul_f32_e32 v101, v97, v97
	v_max_f32_e32 v97, 0, v102
	v_mul_f32_e32 v102, v98, v98
	v_max_f32_e32 v98, 0, v103
	v_max_f32_e32 v99, 0, v99
	v_mul_f32_e32 v100, v100, v100
	v_mul_f32_e32 v97, v97, v97
	v_mul_f32_e32 v98, v98, v98
	v_mul_f32_e32 v99, v99, v99
	v_cvt_pk_bf16_f32 v96, v100, v96
	v_cvt_pk_bf16_f32 v97, v97, v98
	v_cvt_pk_bf16_f32 v98, v104, v101
	v_cvt_pk_bf16_f32 v99, v102, v99
	ds_bpermute_b32 v224, v228, v96
	ds_bpermute_b32 v225, v228, v97
	ds_bpermute_b32 v226, v228, v98
	ds_bpermute_b32 v227, v228, v99
	s_waitcnt lgkmcnt(4)
	global_store_dwordx4 v[112:113], v[220:223], off
	s_waitcnt lgkmcnt(0)
	global_store_dwordx4 v[112:113], v[224:227], off offset:256
	s_nop 1
	v_or_b32_e32 v96, 32, v152
	v_ashrrev_i32_e32 v97, 31, v96
	v_lshlrev_b64 v[96:97], 13, v[96:97]
	v_lshl_add_u64 v[96:97], s[78:79], 0, v[96:97]
	v_lshl_add_u64 v[96:97], v[96:97], 0, v[150:151]
	v_mov_b32_e32 v98, v188
	v_pk_mul_f32 v[88:89], v[88:89], v[98:99] op_sel_hi:[1,0]
	v_pk_mul_f32 v[92:93], v[92:93], v[98:99] op_sel_hi:[1,0]
	v_pk_mul_f32 v[90:91], v[90:91], v[98:99] op_sel_hi:[1,0]
	v_max_f32_e32 v88, 0, v88
	v_pk_mul_f32 v[94:95], v[94:95], v[98:99] op_sel_hi:[1,0]
	v_mul_f32_e32 v99, v88, v88
	v_max_f32_e32 v88, 0, v93
	v_max_f32_e32 v89, 0, v89
	v_max_f32_e32 v90, 0, v90
	v_max_f32_e32 v92, 0, v92
	v_mul_f32_e32 v88, v88, v88
	v_mul_f32_e32 v93, v89, v89
	v_max_f32_e32 v89, 0, v94
	v_mul_f32_e32 v94, v90, v90
	v_max_f32_e32 v90, 0, v95
	v_max_f32_e32 v91, 0, v91
	v_pk_mul_f32 v[80:81], v[80:81], v[98:99] op_sel_hi:[1,0]
	v_mul_f32_e32 v92, v92, v92
	v_mul_f32_e32 v89, v89, v89
	v_mul_f32_e32 v90, v90, v90
	v_mul_f32_e32 v91, v91, v91
	v_cvt_pk_bf16_f32 v88, v92, v88
	v_pk_mul_f32 v[84:85], v[84:85], v[98:99] op_sel_hi:[1,0]
	v_pk_mul_f32 v[82:83], v[82:83], v[98:99] op_sel_hi:[1,0]
	v_max_f32_e32 v80, 0, v80
	v_cvt_pk_bf16_f32 v89, v89, v90
	v_cvt_pk_bf16_f32 v90, v99, v93
	v_cvt_pk_bf16_f32 v91, v94, v91
	ds_bpermute_b32 v220, v228, v88
	ds_bpermute_b32 v221, v228, v89
	ds_bpermute_b32 v222, v228, v90
	ds_bpermute_b32 v223, v228, v91
	v_pk_mul_f32 v[86:87], v[86:87], v[98:99] op_sel_hi:[1,0]
	v_max_f32_e32 v81, 0, v81
	v_mul_f32_e32 v88, v80, v80
	v_max_f32_e32 v80, 0, v85
	v_max_f32_e32 v82, 0, v82
	v_max_f32_e32 v84, 0, v84
	v_mul_f32_e32 v80, v80, v80
	v_mul_f32_e32 v85, v81, v81
	v_max_f32_e32 v81, 0, v86
	v_mul_f32_e32 v86, v82, v82
	v_max_f32_e32 v82, 0, v87
	v_max_f32_e32 v83, 0, v83
	v_mul_f32_e32 v84, v84, v84
	v_mul_f32_e32 v81, v81, v81
	v_mul_f32_e32 v82, v82, v82
	v_mul_f32_e32 v83, v83, v83
	v_cvt_pk_bf16_f32 v80, v84, v80
	v_cvt_pk_bf16_f32 v81, v81, v82
	v_cvt_pk_bf16_f32 v82, v88, v85
	v_cvt_pk_bf16_f32 v83, v86, v83
	ds_bpermute_b32 v224, v228, v80
	ds_bpermute_b32 v225, v228, v81
	ds_bpermute_b32 v226, v228, v82
	ds_bpermute_b32 v227, v228, v83
	s_waitcnt lgkmcnt(4)
	global_store_dwordx4 v[96:97], v[220:223], off
	s_waitcnt lgkmcnt(0)
; __device__ __forceinline__ unsigned cvt_pk_bf16(float lo, float hi) { unsigned r; asm volatile("v_cvt_pk_bf16_f32 %0, %1, %2" : "=v"(r) : "v"(lo), "v"(hi)); return r; }
;     __device__ __forceinline__ void operator()(const f32x4 (&acc)[2][2][4][2], const Unit& u, int wr, int wc, int fr, int fq) const {
;     ...
;                 const int row = row0 + ai * HALF + m * 16;
;                 const f32x4* sp = (const f32x4*)(ss + (size_t)row * 16);
;                 const f32x4 a0 = sp[0], a1 = sp[1], a2 = sp[2], a3 = sp[3];
;                 const float tot = ((a0.x + a0.y) + (a0.z + a0.w)) + ((a1.x + a1.y) + (a1.z + a1.w)) + ((a2.x + a2.y) + (a2.z + a2.w)) + ((a3.x + a3.y) + (a3.z + a3.w));
;                 const float rs = rsqrtf(tot * (1.0f / 1024.0f) + 1e-6f);
;                 bf16_t* rowp = O + (size_t)row * ldc + col0;
; #pragma unroll
;                 for (int bj = 0; bj < 2; ++bj) {
;                     f32x4 v0 = acc[ai][bj][m][0] * rs, v1 = acc[ai][bj][m][1] * rs;
;                     if (ACT == 1) {
; #pragma unroll
;                         for (int e = 0; e < 4; ++e) { float a = fmaxf(v0[e], 0.f); v0[e] = a * a; float b = fmaxf(v1[e], 0.f); v1[e] = b * b; }
;                     }
;                     u32x4 w; w.x = cvt_pk_bf16(v0[0], v0[1]); w.y = cvt_pk_bf16(v0[2], v0[3]); w.z = cvt_pk_bf16(v1[0], v1[1]); w.w = cvt_pk_bf16(v1[2], v1[3]);
;                     *(u32x4*)(rowp + bj * HALF) = w;
	global_store_dwordx4 v[96:97], v[224:227], off offset:256
	s_nop 1
	v_or_b32_e32 v80, 48, v152
	v_ashrrev_i32_e32 v81, 31, v80
	v_lshlrev_b64 v[80:81], 13, v[80:81]
	v_lshl_add_u64 v[80:81], s[78:79], 0, v[80:81]
	v_lshl_add_u64 v[80:81], v[80:81], 0, v[150:151]
	v_mov_b32_e32 v82, v192
	v_pk_mul_f32 v[72:73], v[72:73], v[82:83] op_sel_hi:[1,0]
	v_pk_mul_f32 v[76:77], v[76:77], v[82:83] op_sel_hi:[1,0]
	v_pk_mul_f32 v[74:75], v[74:75], v[82:83] op_sel_hi:[1,0]
	v_max_f32_e32 v72, 0, v72
	v_pk_mul_f32 v[78:79], v[78:79], v[82:83] op_sel_hi:[1,0]
	v_mul_f32_e32 v83, v72, v72
	v_max_f32_e32 v72, 0, v77
	v_max_f32_e32 v73, 0, v73
	v_max_f32_e32 v74, 0, v74
	v_max_f32_e32 v76, 0, v76
	v_mul_f32_e32 v72, v72, v72
	v_mul_f32_e32 v77, v73, v73
	v_max_f32_e32 v73, 0, v78
	v_mul_f32_e32 v78, v74, v74
	v_max_f32_e32 v74, 0, v79
	v_max_f32_e32 v75, 0, v75
	v_pk_mul_f32 v[64:65], v[64:65], v[82:83] op_sel_hi:[1,0]
	v_mul_f32_e32 v76, v76, v76
	v_mul_f32_e32 v73, v73, v73
	v_mul_f32_e32 v74, v74, v74
	v_mul_f32_e32 v75, v75, v75
	v_cvt_pk_bf16_f32 v72, v76, v72
	v_pk_mul_f32 v[68:69], v[68:69], v[82:83] op_sel_hi:[1,0]
	v_pk_mul_f32 v[66:67], v[66:67], v[82:83] op_sel_hi:[1,0]
	v_max_f32_e32 v64, 0, v64
	v_cvt_pk_bf16_f32 v73, v73, v74
	v_cvt_pk_bf16_f32 v74, v83, v77
	v_cvt_pk_bf16_f32 v75, v78, v75
	ds_bpermute_b32 v220, v228, v72
	ds_bpermute_b32 v221, v228, v73
	ds_bpermute_b32 v222, v228, v74
	ds_bpermute_b32 v223, v228, v75
	v_pk_mul_f32 v[70:71], v[70:71], v[82:83] op_sel_hi:[1,0]
	v_max_f32_e32 v65, 0, v65
	v_mul_f32_e32 v72, v64, v64
	v_max_f32_e32 v64, 0, v69
	v_max_f32_e32 v66, 0, v66
	v_max_f32_e32 v68, 0, v68
	v_mul_f32_e32 v64, v64, v64
	v_mul_f32_e32 v69, v65, v65
	v_max_f32_e32 v65, 0, v70
	v_mul_f32_e32 v70, v66, v66
	v_max_f32_e32 v66, 0, v71
	v_max_f32_e32 v67, 0, v67
	v_mul_f32_e32 v68, v68, v68
	v_mul_f32_e32 v65, v65, v65
	v_mul_f32_e32 v66, v66, v66
	v_mul_f32_e32 v67, v67, v67
	v_cvt_pk_bf16_f32 v64, v68, v64
	v_cvt_pk_bf16_f32 v65, v65, v66
	v_cvt_pk_bf16_f32 v66, v72, v69
	v_cvt_pk_bf16_f32 v67, v70, v67
	ds_bpermute_b32 v224, v228, v64
	ds_bpermute_b32 v225, v228, v65
	ds_bpermute_b32 v226, v228, v66
	ds_bpermute_b32 v227, v228, v67
	s_waitcnt lgkmcnt(4)
	global_store_dwordx4 v[80:81], v[220:223], off
	s_waitcnt lgkmcnt(0)
	global_store_dwordx4 v[80:81], v[224:227], off offset:256
	s_nop 1
	v_add_u32_e32 v64, 0x80, v152
	v_ashrrev_i32_e32 v65, 31, v64
	v_lshlrev_b64 v[64:65], 13, v[64:65]
	v_lshl_add_u64 v[64:65], s[78:79], 0, v[64:65]
	v_lshl_add_u64 v[64:65], v[64:65], 0, v[150:151]
	s_waitcnt vmcnt(8)
	v_add_f32_e32 v196, v196, v197
	v_add_f32_e32 v198, v198, v199
	v_add_f32_e32 v208, v208, v209
	v_add_f32_e32 v210, v210, v211
	v_add_f32_e32 v212, v212, v213
	v_add_f32_e32 v214, v214, v215
	v_add_f32_e32 v216, v216, v217
	v_add_f32_e32 v218, v218, v219
	v_add_f32_e32 v196, v196, v198
	v_add_f32_e32 v208, v208, v210
	v_add_f32_e32 v212, v212, v214
	v_add_f32_e32 v216, v216, v218
	v_mov_b32_e32 v197, v196
	v_mov_b32_e32 v209, v208
	v_mov_b32_e32 v213, v212
	v_mov_b32_e32 v217, v216
	s_nop 1
	v_permlane16_swap_b32_e32 v196, v197
	v_permlane16_swap_b32_e32 v208, v209
	v_permlane16_swap_b32_e32 v212, v213
	v_permlane16_swap_b32_e32 v216, v217
	v_add_f32_e32 v196, v196, v197
	v_add_f32_e32 v208, v208, v209
	v_add_f32_e32 v212, v212, v213
	v_add_f32_e32 v216, v216, v217
	v_mov_b32_e32 v197, v196
	v_mov_b32_e32 v209, v208
	v_mov_b32_e32 v213, v212
	v_mov_b32_e32 v217, v216
	s_nop 1
	v_permlane32_swap_b32_e32 v196, v197
	v_permlane32_swap_b32_e32 v208, v209
	v_permlane32_swap_b32_e32 v212, v213
	v_permlane32_swap_b32_e32 v216, v217
	v_add_f32_e32 v196, v196, v197
	v_add_f32_e32 v208, v208, v209
	v_add_f32_e32 v212, v212, v213
	v_add_f32_e32 v216, v216, v217
	v_fmamk_f32 v196, v196, 0x3a800000, v137
	v_cmp_gt_f32_e32 vcc, s4, v196
	v_mul_f32_e32 v197, 0x4b800000, v196
	s_nop 0
	v_cndmask_b32_e32 v196, v196, v197, vcc
	v_rsq_f32_e32 v196, v196
	s_nop 0
	v_mul_f32_e32 v197, 0x45800000, v196
	v_cndmask_b32_e32 v196, v196, v197, vcc
	v_fmamk_f32 v208, v208, 0x3a800000, v137
	v_cmp_gt_f32_e32 vcc, s4, v208
	v_mul_f32_e32 v209, 0x4b800000, v208
	s_nop 0
	v_cndmask_b32_e32 v208, v208, v209, vcc
	v_rsq_f32_e32 v208, v208
	s_nop 0
	v_mul_f32_e32 v209, 0x45800000, v208
	v_cndmask_b32_e32 v208, v208, v209, vcc
	v_fmamk_f32 v212, v212, 0x3a800000, v137
	v_cmp_gt_f32_e32 vcc, s4, v212
	v_mul_f32_e32 v213, 0x4b800000, v212
	s_nop 0
	v_cndmask_b32_e32 v212, v212, v213, vcc
	v_rsq_f32_e32 v212, v212
	s_nop 0
	v_mul_f32_e32 v213, 0x45800000, v212
	v_cndmask_b32_e32 v212, v212, v213, vcc
	v_fmamk_f32 v216, v216, 0x3a800000, v137
	v_cmp_gt_f32_e32 vcc, s4, v216
	v_mul_f32_e32 v217, 0x4b800000, v216
	s_nop 0
	v_cndmask_b32_e32 v216, v216, v217, vcc
	v_rsq_f32_e32 v216, v216
	s_nop 0
	v_mul_f32_e32 v217, 0x45800000, v216
	v_cndmask_b32_e32 v216, v216, v217, vcc
	v_mov_b32_e32 v66, v196
	v_pk_mul_f32 v[56:57], v[56:57], v[66:67] op_sel_hi:[1,0]
	v_pk_mul_f32 v[60:61], v[60:61], v[66:67] op_sel_hi:[1,0]
	v_pk_mul_f32 v[58:59], v[58:59], v[66:67] op_sel_hi:[1,0]
	v_max_f32_e32 v56, 0, v56
	v_pk_mul_f32 v[62:63], v[62:63], v[66:67] op_sel_hi:[1,0]
	v_mul_f32_e32 v67, v56, v56
	v_max_f32_e32 v56, 0, v61
	v_max_f32_e32 v57, 0, v57
	v_max_f32_e32 v58, 0, v58
	v_max_f32_e32 v60, 0, v60
	v_mul_f32_e32 v56, v56, v56
	v_mul_f32_e32 v61, v57, v57
	v_max_f32_e32 v57, 0, v62
	v_mul_f32_e32 v62, v58, v58
	v_max_f32_e32 v58, 0, v63
	v_max_f32_e32 v59, 0, v59
	v_pk_mul_f32 v[48:49], v[48:49], v[66:67] op_sel_hi:[1,0]
	v_mul_f32_e32 v60, v60, v60
	v_mul_f32_e32 v57, v57, v57
	v_mul_f32_e32 v58, v58, v58
	v_mul_f32_e32 v59, v59, v59
	v_cvt_pk_bf16_f32 v56, v60, v56
	v_pk_mul_f32 v[52:53], v[52:53], v[66:67] op_sel_hi:[1,0]
	v_pk_mul_f32 v[50:51], v[50:51], v[66:67] op_sel_hi:[1,0]
	v_max_f32_e32 v48, 0, v48
	v_cvt_pk_bf16_f32 v57, v57, v58
	v_cvt_pk_bf16_f32 v58, v67, v61
	v_cvt_pk_bf16_f32 v59, v62, v59
	ds_bpermute_b32 v220, v228, v56
	ds_bpermute_b32 v221, v228, v57
	ds_bpermute_b32 v222, v228, v58
	ds_bpermute_b32 v223, v228, v59
	v_pk_mul_f32 v[54:55], v[54:55], v[66:67] op_sel_hi:[1,0]
	v_max_f32_e32 v49, 0, v49
	v_mul_f32_e32 v56, v48, v48
	v_max_f32_e32 v48, 0, v53
	v_max_f32_e32 v50, 0, v50
	v_max_f32_e32 v52, 0, v52
	v_mul_f32_e32 v48, v48, v48
	v_mul_f32_e32 v53, v49, v49
	v_max_f32_e32 v49, 0, v54
	v_mul_f32_e32 v54, v50, v50
	v_max_f32_e32 v50, 0, v55
	v_max_f32_e32 v51, 0, v51
	v_mul_f32_e32 v52, v52, v52
	v_mul_f32_e32 v49, v49, v49
	v_mul_f32_e32 v50, v50, v50
	v_mul_f32_e32 v51, v51, v51
	v_cvt_pk_bf16_f32 v48, v52, v48
	v_cvt_pk_bf16_f32 v49, v49, v50
	v_cvt_pk_bf16_f32 v50, v56, v53
	v_cvt_pk_bf16_f32 v51, v54, v51
	ds_bpermute_b32 v224, v228, v48
	ds_bpermute_b32 v225, v228, v49
	ds_bpermute_b32 v226, v228, v50
	ds_bpermute_b32 v227, v228, v51
	s_waitcnt lgkmcnt(4)
; __device__ __forceinline__ unsigned cvt_pk_bf16(float lo, float hi) { unsigned r; asm volatile("v_cvt_pk_bf16_f32 %0, %1, %2" : "=v"(r) : "v"(lo), "v"(hi)); return r; }
; #define PG8_BAR __builtin_amdgcn_s_barrier()
;     __device__ __forceinline__ void operator()(const f32x4 (&acc)[2][2][4][2], const Unit& u, int wr, int wc, int fr, int fq) const {
;     ...
;                 const int row = row0 + ai * HALF + m * 16;
;                 const f32x4* sp = (const f32x4*)(ss + (size_t)row * 16);
;                 const f32x4 a0 = sp[0], a1 = sp[1], a2 = sp[2], a3 = sp[3];
;                 const float tot = ((a0.x + a0.y) + (a0.z + a0.w)) + ((a1.x + a1.y) + (a1.z + a1.w)) + ((a2.x + a2.y) + (a2.z + a2.w)) + ((a3.x + a3.y) + (a3.z + a3.w));
;                 const float rs = rsqrtf(tot * (1.0f / 1024.0f) + 1e-6f);
;                 bf16_t* rowp = O + (size_t)row * ldc + col0;
; #pragma unroll
;                 for (int bj = 0; bj < 2; ++bj) {
;                     f32x4 v0 = acc[ai][bj][m][0] * rs, v1 = acc[ai][bj][m][1] * rs;
;                     if (ACT == 1) {
; #pragma unroll
;                         for (int e = 0; e < 4; ++e) { float a = fmaxf(v0[e], 0.f); v0[e] = a * a; float b = fmaxf(v1[e], 0.f); v1[e] = b * b; }
;                     }
;                     u32x4 w; w.x = cvt_pk_bf16(v0[0], v0[1]); w.y = cvt_pk_bf16(v0[2], v0[3]); w.z = cvt_pk_bf16(v1[0], v1[1]); w.w = cvt_pk_bf16(v1[2], v1[3]);
;                     *(u32x4*)(rowp + bj * HALF) = w;
; template <class Epi, class Sched, bool ALIGN_EPI = false, bool SP2 = false>
; __device__ __forceinline__ void gemm_phase(PG8_LAS unsigned char* lds, const Gemm g, const Sched& S, const Epi& E) {
;     ...
;         cur = nxt; cA = nA; cB = nB; ++ui;
;         if constexpr (ALIGN_EPI) { if (wr == 1) PG8_BAR; }
	global_store_dwordx4 v[64:65], v[220:223], off
	s_waitcnt lgkmcnt(0)
	global_store_dwordx4 v[64:65], v[224:227], off offset:256
	s_nop 1
	v_add_u32_e32 v48, 0x90, v152
	v_ashrrev_i32_e32 v49, 31, v48
	v_lshlrev_b64 v[48:49], 13, v[48:49]
	v_lshl_add_u64 v[48:49], s[78:79], 0, v[48:49]
	v_lshl_add_u64 v[48:49], v[48:49], 0, v[150:151]
	v_mov_b32_e32 v50, v208
	v_pk_mul_f32 v[40:41], v[40:41], v[50:51] op_sel_hi:[1,0]
	v_pk_mul_f32 v[44:45], v[44:45], v[50:51] op_sel_hi:[1,0]
	v_pk_mul_f32 v[42:43], v[42:43], v[50:51] op_sel_hi:[1,0]
	v_max_f32_e32 v40, 0, v40
	v_pk_mul_f32 v[46:47], v[46:47], v[50:51] op_sel_hi:[1,0]
	v_mul_f32_e32 v51, v40, v40
	v_max_f32_e32 v40, 0, v45
	v_max_f32_e32 v41, 0, v41
	v_max_f32_e32 v42, 0, v42
	v_max_f32_e32 v44, 0, v44
	v_mul_f32_e32 v40, v40, v40
	v_mul_f32_e32 v45, v41, v41
	v_max_f32_e32 v41, 0, v46
	v_mul_f32_e32 v46, v42, v42
	v_max_f32_e32 v42, 0, v47
	v_max_f32_e32 v43, 0, v43
	v_pk_mul_f32 v[32:33], v[32:33], v[50:51] op_sel_hi:[1,0]
	v_mul_f32_e32 v44, v44, v44
	v_mul_f32_e32 v41, v41, v41
	v_mul_f32_e32 v42, v42, v42
	v_mul_f32_e32 v43, v43, v43
	v_cvt_pk_bf16_f32 v40, v44, v40
	v_pk_mul_f32 v[36:37], v[36:37], v[50:51] op_sel_hi:[1,0]
	v_pk_mul_f32 v[34:35], v[34:35], v[50:51] op_sel_hi:[1,0]
	v_max_f32_e32 v32, 0, v32
	v_cvt_pk_bf16_f32 v41, v41, v42
	v_cvt_pk_bf16_f32 v42, v51, v45
	v_cvt_pk_bf16_f32 v43, v46, v43
	ds_bpermute_b32 v220, v228, v40
	ds_bpermute_b32 v221, v228, v41
	ds_bpermute_b32 v222, v228, v42
	ds_bpermute_b32 v223, v228, v43
	v_pk_mul_f32 v[38:39], v[38:39], v[50:51] op_sel_hi:[1,0]
	v_max_f32_e32 v33, 0, v33
	v_mul_f32_e32 v40, v32, v32
	v_max_f32_e32 v32, 0, v37
	v_max_f32_e32 v34, 0, v34
	v_max_f32_e32 v36, 0, v36
	v_mul_f32_e32 v32, v32, v32
	v_mul_f32_e32 v37, v33, v33
	v_max_f32_e32 v33, 0, v38
	v_mul_f32_e32 v38, v34, v34
	v_max_f32_e32 v34, 0, v39
	v_max_f32_e32 v35, 0, v35
	v_mul_f32_e32 v36, v36, v36
	v_mul_f32_e32 v33, v33, v33
	v_mul_f32_e32 v34, v34, v34
	v_mul_f32_e32 v35, v35, v35
	v_cvt_pk_bf16_f32 v32, v36, v32
	v_cvt_pk_bf16_f32 v33, v33, v34
	v_cvt_pk_bf16_f32 v34, v40, v37
	v_cvt_pk_bf16_f32 v35, v38, v35
	ds_bpermute_b32 v224, v228, v32
	ds_bpermute_b32 v225, v228, v33
	ds_bpermute_b32 v226, v228, v34
	ds_bpermute_b32 v227, v228, v35
	s_waitcnt lgkmcnt(4)
	global_store_dwordx4 v[48:49], v[220:223], off
	s_waitcnt lgkmcnt(0)
	global_store_dwordx4 v[48:49], v[224:227], off offset:256
	s_nop 1
	v_add_u32_e32 v32, 0xa0, v152
	v_ashrrev_i32_e32 v33, 31, v32
	v_lshlrev_b64 v[32:33], 13, v[32:33]
	v_lshl_add_u64 v[32:33], s[78:79], 0, v[32:33]
	v_lshl_add_u64 v[32:33], v[32:33], 0, v[150:151]
	v_mov_b32_e32 v34, v212
	v_pk_mul_f32 v[24:25], v[24:25], v[34:35] op_sel_hi:[1,0]
	v_pk_mul_f32 v[28:29], v[28:29], v[34:35] op_sel_hi:[1,0]
	v_pk_mul_f32 v[26:27], v[26:27], v[34:35] op_sel_hi:[1,0]
	v_max_f32_e32 v24, 0, v24
	v_pk_mul_f32 v[30:31], v[30:31], v[34:35] op_sel_hi:[1,0]
	v_mul_f32_e32 v35, v24, v24
	v_max_f32_e32 v24, 0, v29
	v_max_f32_e32 v25, 0, v25
	v_max_f32_e32 v26, 0, v26
	v_max_f32_e32 v28, 0, v28
	v_mul_f32_e32 v24, v24, v24
	v_mul_f32_e32 v29, v25, v25
	v_max_f32_e32 v25, 0, v30
	v_mul_f32_e32 v30, v26, v26
	v_max_f32_e32 v26, 0, v31
	v_max_f32_e32 v27, 0, v27
	v_pk_mul_f32 v[16:17], v[16:17], v[34:35] op_sel_hi:[1,0]
	v_mul_f32_e32 v28, v28, v28
	v_mul_f32_e32 v25, v25, v25
	v_mul_f32_e32 v26, v26, v26
	v_mul_f32_e32 v27, v27, v27
	v_cvt_pk_bf16_f32 v24, v28, v24
	v_pk_mul_f32 v[20:21], v[20:21], v[34:35] op_sel_hi:[1,0]
	v_pk_mul_f32 v[18:19], v[18:19], v[34:35] op_sel_hi:[1,0]
	v_max_f32_e32 v16, 0, v16
	v_cvt_pk_bf16_f32 v25, v25, v26
	v_cvt_pk_bf16_f32 v26, v35, v29
	v_cvt_pk_bf16_f32 v27, v30, v27
	ds_bpermute_b32 v220, v228, v24
	ds_bpermute_b32 v221, v228, v25
	ds_bpermute_b32 v222, v228, v26
	ds_bpermute_b32 v223, v228, v27
	v_pk_mul_f32 v[22:23], v[22:23], v[34:35] op_sel_hi:[1,0]
	v_max_f32_e32 v17, 0, v17
	v_mul_f32_e32 v24, v16, v16
	v_max_f32_e32 v16, 0, v21
	v_max_f32_e32 v18, 0, v18
	v_max_f32_e32 v20, 0, v20
	v_mul_f32_e32 v16, v16, v16
	v_mul_f32_e32 v21, v17, v17
	v_max_f32_e32 v17, 0, v22
	v_mul_f32_e32 v22, v18, v18
	v_max_f32_e32 v18, 0, v23
	v_max_f32_e32 v19, 0, v19
	v_mul_f32_e32 v20, v20, v20
	v_mul_f32_e32 v17, v17, v17
	v_mul_f32_e32 v18, v18, v18
	v_mul_f32_e32 v19, v19, v19
	v_cvt_pk_bf16_f32 v16, v20, v16
	v_cvt_pk_bf16_f32 v17, v17, v18
	v_cvt_pk_bf16_f32 v18, v24, v21
	v_cvt_pk_bf16_f32 v19, v22, v19
	ds_bpermute_b32 v224, v228, v16
	ds_bpermute_b32 v225, v228, v17
	ds_bpermute_b32 v226, v228, v18
	ds_bpermute_b32 v227, v228, v19
	s_waitcnt lgkmcnt(4)
	global_store_dwordx4 v[32:33], v[220:223], off
	s_waitcnt lgkmcnt(0)
	global_store_dwordx4 v[32:33], v[224:227], off offset:256
	s_nop 1
	v_add_u32_e32 v16, 0xb0, v152
	v_ashrrev_i32_e32 v17, 31, v16
	v_lshlrev_b64 v[16:17], 13, v[16:17]
	v_lshl_add_u64 v[16:17], s[78:79], 0, v[16:17]
	v_lshl_add_u64 v[16:17], v[16:17], 0, v[150:151]
	v_mov_b32_e32 v18, v216
	v_pk_mul_f32 v[8:9], v[8:9], v[18:19] op_sel_hi:[1,0]
	v_pk_mul_f32 v[12:13], v[12:13], v[18:19] op_sel_hi:[1,0]
	v_pk_mul_f32 v[10:11], v[10:11], v[18:19] op_sel_hi:[1,0]
	v_max_f32_e32 v8, 0, v8
	v_pk_mul_f32 v[14:15], v[14:15], v[18:19] op_sel_hi:[1,0]
	v_mul_f32_e32 v19, v8, v8
	v_max_f32_e32 v8, 0, v13
	v_max_f32_e32 v9, 0, v9
	v_max_f32_e32 v10, 0, v10
	v_max_f32_e32 v12, 0, v12
	v_mul_f32_e32 v8, v8, v8
	v_mul_f32_e32 v13, v9, v9
	v_max_f32_e32 v9, 0, v14
	v_mul_f32_e32 v14, v10, v10
	v_max_f32_e32 v10, 0, v15
	v_max_f32_e32 v11, 0, v11
	v_pk_mul_f32 v[2:3], v[2:3], v[18:19] op_sel_hi:[1,0]
	v_pk_mul_f32 v[0:1], v[0:1], v[18:19] op_sel_hi:[1,0]
	v_mul_f32_e32 v12, v12, v12
	v_mul_f32_e32 v9, v9, v9
	v_mul_f32_e32 v10, v10, v10
	v_mul_f32_e32 v11, v11, v11
	v_cvt_pk_bf16_f32 v8, v12, v8
	v_pk_mul_f32 v[6:7], v[6:7], v[18:19] op_sel_hi:[1,0]
	v_pk_mul_f32 v[4:5], v[4:5], v[18:19] op_sel_hi:[1,0]
	v_max_f32_e32 v0, 0, v0
	v_max_f32_e32 v1, 0, v1
	v_max_f32_e32 v2, 0, v2
	v_cvt_pk_bf16_f32 v9, v9, v10
	v_cvt_pk_bf16_f32 v10, v19, v13
	v_cvt_pk_bf16_f32 v11, v14, v11
	ds_bpermute_b32 v220, v228, v8
	ds_bpermute_b32 v221, v228, v9
	ds_bpermute_b32 v222, v228, v10
	ds_bpermute_b32 v223, v228, v11
	v_max_f32_e32 v3, 0, v3
	v_max_f32_e32 v4, 0, v4
	v_mul_f32_e32 v8, v0, v0
	v_max_f32_e32 v0, 0, v5
	v_mul_f32_e32 v5, v1, v1
	v_max_f32_e32 v1, 0, v6
	v_mul_f32_e32 v6, v2, v2
	v_max_f32_e32 v2, 0, v7
	v_mul_f32_e32 v0, v0, v0
	v_mul_f32_e32 v1, v1, v1
	v_mul_f32_e32 v2, v2, v2
	v_mul_f32_e32 v3, v3, v3
	s_andn2_b64 vcc, exec, s[38:39]
	v_mul_f32_e32 v4, v4, v4
	v_cvt_pk_bf16_f32 v0, v4, v0
	v_cvt_pk_bf16_f32 v1, v1, v2
	v_cvt_pk_bf16_f32 v2, v8, v5
	v_cvt_pk_bf16_f32 v3, v6, v3
	ds_bpermute_b32 v224, v228, v0
	ds_bpermute_b32 v225, v228, v1
	ds_bpermute_b32 v226, v228, v2
	ds_bpermute_b32 v227, v228, v3
	s_waitcnt lgkmcnt(4)
	global_store_dwordx4 v[16:17], v[220:223], off
	s_waitcnt lgkmcnt(0)
	global_store_dwordx4 v[16:17], v[224:227], off offset:256
	s_cbranch_vccnz .LBB0_1144
	s_andn2_b64 vcc, exec, s[0:1]
	s_setprio 1
	s_cbranch_vccnz .LBB0_1143
	s_setprio 0
	s_barrier
	s_branch .LBB0_1143

; #define PG8_STAGE(bufoff, gbase, voff) do { _Pragma("unroll") for (int _i = 0; _i < 2; ++_i) \
;         __builtin_amdgcn_global_load_lds((const unsigned*)((const char*)(gbase) + (voff)[_i]), (PG8_LAS unsigned*)(lds + (bufoff) + ldsw + _i * 8192), 16, 0, 0); } while (0)
; #define PG8_BAR __builtin_amdgcn_s_barrier()
; template <class Epi, class Sched, bool ALIGN_EPI = false, bool SP2 = false>
; __device__ __forceinline__ void gemm_phase(PG8_LAS unsigned char* lds, const Gemm g, const Sched& S, const Epi& E) {
;     ...
;     const int tid = tid_l, wid = __builtin_amdgcn_readfirstlane(tid >> 6), lane = tid & 63, wr = wid >> 2, wc = wid & 3, fr = lane & 15, fq = lane >> 4;
;     const int K = g.K, nt = K / BK;
;     unsigned voffA[2], voffB[2];
; #pragma unroll
;     for (int i = 0; i < 2; ++i) { int R, C; stage_rc(tid * 16 + i * 8192, R, C); const int Rb = Epi::PERM ? ((R & ~31) + perm32(R & 31)) : R;
;         voffA[i] = (unsigned)(R * K + C) * 2u; voffB[i] = (unsigned)(Rb * K + C) * 2u; }
;     const size_t kstep = (size_t)(BK * 2);
;     const size_t hstep = (size_t)HALF * K * 2;
;     const size_t tstep = 2 * hstep;
;     const unsigned ldsw = (unsigned)wid * 1024u;
;     const int aoff = lds_byte(wr * 64 + fr, fq * 8), boff = lds_byte(wc * 32 + fr, fq * 8);
;     ...
;     const char* cA = (const char*)g.A + (size_t)cur.pm * tstep; const char* cB = (const char*)g.Bt + (size_t)cur.pn * tstep;
;     S.a_ready(cur);
;     if constexpr (SP2) {
;         PG8_STAGE(PG8_SB(0, 0), cB, voffB); PG8_STAGE(PG8_SB(0, 1), cB + hstep, voffB); PG8_STAGE(PG8_SA(0, 0), cA, voffA); PG8_STAGE(PG8_SA(0, 1), cA + hstep, voffA);
;         if (wr == 1) PG8_BAR;
.LBB0_1215:
	s_andn2_b64 vcc, exec, s[0:1]
	s_cbranch_vccnz .LBB0_413
	v_mov_b32_e32 v10, v204
	s_and_b64 vcc, exec, s[48:49]
	v_readfirstlane_b32 s24, v10
	s_cbranch_vccnz .LBB0_1284
	v_lshlrev_b32_e32 v0, 4, v10
	s_waitcnt lgkmcnt(0)
	v_add_u32_e32 v1, 0x2000, v0
	v_ashrrev_i32_e32 v2, 31, v1
	v_lshrrev_b32_e32 v2, 22, v2
	v_add_u32_e32 v2, v1, v2
	v_ashrrev_i32_e32 v4, 10, v2
	v_mul_i32_i24_e32 v2, 0x400, v4
	v_sub_u32_e32 v1, v1, v2
	v_lshrrev_b32_e32 v2, 4, v1
	v_bitop3_b32 v1, v2, v1, 32 bitop3:0x6c
	v_ashrrev_i32_e32 v2, 31, v1
	v_lshrrev_b32_e32 v2, 26, v2
	v_add_u32_e32 v2, v1, v2
	v_lshlrev_b32_e32 v3, 3, v4
	s_lshl_b32 s0, s45, 23
	v_readlane_b32 s1, v251, 32
	v_ashrrev_i32_e32 v5, 6, v2
	v_and_b32_e32 v3, -16, v3
	s_add_u32 s42, s1, s0
	v_readlane_b32 s0, v251, 33
	v_add_u32_e32 v3, v5, v3
	s_addc_u32 s43, s0, 0
	v_and_b32_e32 v6, 3, v5
	s_mov_b32 s0, 0x7ffe0
	v_lshrrev_b32_e32 v7, 2, v3
	v_lshlrev_b32_e32 v8, 1, v3
	v_and_b32_e32 v2, 0xc0, v2
	v_and_or_b32 v6, v3, s0, v6
	v_and_b32_e32 v7, 4, v7
	v_and_b32_e32 v8, 24, v8
	v_sub_u32_e32 v1, v1, v2
	v_or3_b32 v7, v6, v7, v8
	v_lshlrev_b32_e32 v6, 5, v4
	v_ashrrev_i16_sdwa v1, v205, sext(v1) dst_sel:DWORD dst_unused:UNUSED_PAD src0_sel:DWORD src1_sel:BYTE_0
	v_and_b32_e32 v8, 32, v6
	v_bfe_i32 v6, v1, 0, 16
	v_add_lshl_u32 v1, v8, v6, 1
	v_lshl_add_u32 v128, v7, 13, v1
	v_lshl_add_u32 v130, v3, 13, v1
	v_bfe_i32 v1, v10, 27, 1
	v_lshrrev_b32_e32 v1, 22, v1
	v_add_u32_e32 v1, v0, v1
	v_and_b32_e32 v1, 0xfffffc00, v1
	v_sub_u32_e32 v0, v0, v1
	v_lshrrev_b32_e32 v1, 4, v0
	v_ashrrev_i32_e32 v2, 31, v10
	v_bitop3_b32 v0, v1, v0, 32 bitop3:0x6c
	v_lshrrev_b32_e32 v2, 26, v2
	v_ashrrev_i32_e32 v1, 31, v0
	v_add_u32_e32 v2, v10, v2
	v_lshrrev_b32_e32 v1, 26, v1
	v_ashrrev_i32_e32 v8, 6, v2
	v_add_u32_e32 v1, v0, v1
	v_lshlrev_b32_e32 v2, 3, v8
	v_ashrrev_i32_e32 v7, 6, v1
	v_and_b32_e32 v2, -16, v2
	v_add_u32_e32 v2, v7, v2
	v_and_b32_e32 v3, 3, v7
	v_lshrrev_b32_e32 v9, 2, v2
	v_lshlrev_b32_e32 v11, 1, v2
	v_and_b32_e32 v1, 0xc0, v1
	s_ashr_i32 s25, s24, 6
	v_and_or_b32 v3, v2, s0, v3
	v_and_b32_e32 v9, 4, v9
	v_and_b32_e32 v11, 24, v11
	v_sub_u32_e32 v0, v0, v1
	s_ashr_i32 s1, s24, 8
	s_lshl_b32 s54, s25, 10
	v_or3_b32 v3, v3, v9, v11
	v_lshlrev_b32_e32 v9, 5, v8
	v_ashrrev_i16_sdwa v0, v205, sext(v0) dst_sel:DWORD dst_unused:UNUSED_PAD src0_sel:DWORD src1_sel:BYTE_0
	v_readlane_b32 s22, v251, 54
	v_and_b32_e32 v11, 32, v9
	v_bfe_i32 v9, v0, 0, 16
	v_readlane_b32 s23, v251, 55
	s_add_u32 s26, s42, s22
	v_add_lshl_u32 v0, v11, v9, 1
	s_addc_u32 s27, s43, s23
	s_add_i32 s55, s54, 0
	v_lshl_add_u32 v132, v3, 13, v0
	s_add_i32 m0, s55, 0x10000
	v_lshl_add_u32 v134, v2, 13, v0
	global_load_lds_dwordx4 v132, s[26:27]
	s_add_i32 m0, s55, 0x12000
	s_add_u32 s22, s26, 0x100000
	global_load_lds_dwordx4 v128, s[26:27]
	s_addc_u32 s23, s27, 0
	s_add_i32 m0, s55, 0x14000
	s_add_i32 s88, s55, 0x2000
	global_load_lds_dwordx4 v132, s[22:23]
	s_add_i32 m0, s55, 0x16000
	v_writelane_b32 v250, s95, 34
	global_load_lds_dwordx4 v128, s[22:23]
	v_readlane_b32 s22, v251, 62
	s_mov_b32 m0, s55
	v_readlane_b32 s23, v251, 63
	s_add_i32 s89, s55, 0x4000
	s_add_i32 s30, s55, 0x6000
	s_cmp_eq_u32 s1, 1
	v_mov_b32_e32 v133, v139
	v_mov_b32_e32 v129, v139
	global_load_lds_dwordx4 v134, s[22:23]
	s_mov_b32 m0, s88
	v_lshl_add_u64 v[0:1], s[26:27], 0, v[132:133]
	global_load_lds_dwordx4 v130, s[22:23]
	v_readlane_b32 s22, v250, 0
	s_mov_b32 m0, s89
	v_readlane_b32 s23, v250, 1
	v_lshl_add_u64 v[2:3], s[26:27], 0, v[128:129]
	s_nop 3
	global_load_lds_dwordx4 v134, s[22:23]
	s_mov_b32 m0, s30
	s_nop 0
	global_load_lds_dwordx4 v130, s[22:23]
	s_cselect_b64 s[22:23], -1, 0
	v_writelane_b32 v250, s22, 32
	s_cmp_lg_u32 s1, 1
	s_nop 0
	v_writelane_b32 v250, s23, 33
	s_setprio 1
	s_cbranch_scc1 .LBB0_1219
	s_setprio 0
	s_barrier

; #define PG8_BAR __builtin_amdgcn_s_barrier()
; template <class Epi, class Sched, bool ALIGN_EPI = false, bool SP2 = false>
; __device__ __forceinline__ void gemm_phase(PG8_LAS unsigned char* lds, const Gemm g, const Sched& S, const Epi& E) {
;     ...
;         if constexpr (ALIGN_EPI) { if (wr == 0) PG8_BAR; }
;         if constexpr (!Epi::AFTER_DRAIN) { E(acc, cur, wr, wc, fr, fq); S.done(cur); }
;         if (!has_next) break;
; #pragma unroll
;         for (int a = 0; a < 2; ++a)
; #pragma unroll
;             for (int b = 0; b < 2; ++b)
; #pragma unroll
;                 for (int m = 0; m < 4; ++m)
; #pragma unroll
;                     for (int n = 0; n < 2; ++n) acc[a][b][m][n] = (f32x4){0.f, 0.f, 0.f, 0.f};
;         cur = nxt; cA = nA; cB = nB; ++ui;
;         if constexpr (ALIGN_EPI) { if (wr == 1) PG8_BAR; }
.LBB0_1280:
	s_or_b64 exec, exec, s[24:25]
	s_andn2_b64 vcc, exec, s[38:39]
	s_mov_b64 s[24:25], -1
	s_cbranch_vccnz .LBB0_1221
	v_readlane_b32 s24, v250, 32
	v_readlane_b32 s25, v250, 33
	s_andn2_b64 vcc, exec, s[24:25]
	s_setprio 1
	s_cbranch_vccnz .LBB0_1220
	s_setprio 0
	s_barrier
	s_branch .LBB0_1220
